# attention loops: p0 scaling via v_pk_fma_f32 (8 instead of 16 fmamk), redundant vmcnt ladder / pad nop / 0+x add removed; on top of v36
# speedup vs baseline: 1.0112x; 1.0024x over previous
; __device__ __forceinline__ void finishSM(f32x16& p0, f32x16& p1, float alpha, float& l_reg, bf16x8& pa0, bf16x8& pa1, bf16x8& pa2, bf16x8& pa3) {
; #pragma unroll
;   for (int r = 0; r < 16; ++r) p1[r] = __builtin_amdgcn_exp2f(p1[r]);
;   float ps = 0;
; #pragma unroll
;   for (int r = 0; r < 16; ++r) ps += p0[r];
; #pragma unroll
;   for (int r = 0; r < 16; ++r) ps += p1[r];
;   { auto rr = __builtin_amdgcn_permlane32_swap(__float_as_uint(ps), __float_as_uint(ps), false, false);
;     ps = __uint_as_float(rr[0]) + __uint_as_float(rr[1]); }
;   l_reg = l_reg * alpha + ps;
;     ...
;   PK4(p0, 0, pa0); PK4(p0, 8, pa1); PK4(p1, 0, pa2); PK4(p1, 8, pa3);
;     ...
; }
; template <int DK, int NPARK>
; __device__ __forceinline__ void qkt(f32x16& p0, f32x16& p1, const char* Ks, const bf16x8* qr, const char* qpark, int r32, int hi) {
;   p0 = f32x16{}; p1 = f32x16{};
; #pragma unroll
;   for (int d0 = 0; d0 < DK / 16; ++d0) { const int cb = (d0 * 16 + hi * 8) * 2;
;     bf16x8 b0 = *reinterpret_cast<const bf16x8*>(Ks + kswz<DK>(r32, cb));
;     bf16x8 b1 = *reinterpret_cast<const bf16x8*>(Ks + kswz<DK>(32 + r32, cb));
;     bf16x8 q;
;     if constexpr (NPARK > 0) { if (d0 >= DK / 16 - NPARK) q = *reinterpret_cast<const bf16x8*>(qpark + (d0 - (DK / 16 - NPARK)) * 1024); else q = qr[d0]; } else q = qr[d0];
;     p0 = __builtin_amdgcn_mfma_f32_32x32x16_bf16(b0, q, p0, 0, 0, 0);
;     p1 = __builtin_amdgcn_mfma_f32_32x32x16_bf16(b1, q, p1, 0, 0, 0); }
; }
; __device__ __forceinline__ int v_st(int k, int c) { const int kk = (k & ~0xC) | ((k & 4) << 1) | ((k & 8) >> 1); return ((kk >> 3) * 4 + (c >> 5)) * 512 + ((kk & 7) * 32 + (c & 31)) * 2; }
; __device__ __forceinline__ int v_rd_base(int lane) { return ((lane & 3) << 3) | (((lane >> 2) & 3) << 6) | (((lane >> 4) & 1) << 5) | (((lane >> 5) & 1) << 8); }
; template <int OFF> __device__ __forceinline__ s16x4 tr_read(int vb) {
;   s16x4 r; asm volatile("ds_read_b64_tr_b16 %0, %1 offset:%2" : "=&v"(r) : "v"(vb), "i"(OFF) : "memory"); return r;
; }
; template <int D0> __device__ __forceinline__ void pv_one(f32x16& od, int vb, bf16x8 pa0, bf16x8 pa1, bf16x8 pa2, bf16x8 pa3) {
;   const s16x4 l0 = tr_read<v_rd_off(D0, 0, 0)>(vb), h0 = tr_read<v_rd_off(D0, 0, 1)>(vb), l1 = tr_read<v_rd_off(D0, 1, 0)>(vb), h1 = tr_read<v_rd_off(D0, 1, 1)>(vb);
.LBB0_924:
	ds_read_b128 v[64:67], v161 offset:49152
	ds_read_b128 v[68:71], v161 offset:57344
	ds_read_b128 v[194:197], v170 offset:49152
	ds_read_b128 v[198:201], v170 offset:57344
	v_add_f32_e32 v144, v187, v145
	s_waitcnt lgkmcnt(3)
	v_mfma_f32_32x32x16_bf16 v[80:95], v[64:67], v[112:115], 0
	v_add_f32_e32 v144, v146, v144
	v_add_f32_e32 v144, v188, v144
	v_add_f32_e32 v144, v186, v144
	v_add_f32_e32 v144, v189, v144
	v_add_f32_e32 v144, v147, v144
	v_add_f32_e32 v144, v185, v144
	v_add_f32_e32 v144, v157, v144
	s_waitcnt lgkmcnt(2)
	v_mfma_f32_32x32x16_bf16 v[64:79], v[68:71], v[112:115], 0
	v_add_f32_e32 v144, v181, v144
	v_add_f32_e32 v144, v179, v144
	v_add_f32_e32 v144, v182, v144
	v_exp_f32_e32 v142, v142
	v_add_f32_e32 v144, v154, v144
	v_exp_f32_e32 v143, v143
	v_add_f32_e32 v144, v155, v144
	s_waitcnt lgkmcnt(1)
	v_mfma_f32_32x32x16_bf16 v[80:95], v[194:197], v[108:111], v[80:95]
	v_exp_f32_e32 v140, v140
	v_add_f32_e32 v144, v156, v144
	v_exp_f32_e32 v141, v141
	v_add_f32_e32 v144, v180, v144
	v_exp_f32_e32 v136, v136
	v_add_f32_e32 v144, v142, v144
	v_exp_f32_e32 v137, v137
	s_waitcnt lgkmcnt(0)
	v_mfma_f32_32x32x16_bf16 v[64:79], v[198:201], v[108:111], v[64:79]
	ds_read_b128 v[194:197], v169 offset:49152
	ds_read_b128 v[198:201], v169 offset:57344
	v_add_f32_e32 v144, v143, v144
	v_exp_f32_e32 v132, v132
	v_add_f32_e32 v144, v140, v144
	v_exp_f32_e32 v133, v133
	v_add_f32_e32 v144, v141, v144
	v_exp_f32_e32 v130, v130
	s_waitcnt lgkmcnt(1)
	v_mfma_f32_32x32x16_bf16 v[80:95], v[194:197], v[120:123], v[80:95]
	v_add_f32_e32 v144, v136, v144
	v_exp_f32_e32 v131, v131
	v_add_f32_e32 v144, v137, v144
	v_exp_f32_e32 v138, v138
	v_add_f32_e32 v144, v132, v144
	v_exp_f32_e32 v139, v139
	v_add_f32_e32 v144, v133, v144
	s_waitcnt lgkmcnt(0)
	v_mfma_f32_32x32x16_bf16 v[64:79], v[198:201], v[120:123], v[64:79]
	ds_read_b128 v[194:197], v168 offset:49152
	ds_read_b128 v[198:201], v168 offset:57344
	v_exp_f32_e32 v134, v134
	v_add_f32_e32 v144, v130, v144
	v_exp_f32_e32 v135, v135
	v_add_f32_e32 v144, v131, v144
	v_exp_f32_e32 v128, v128
	v_add_f32_e32 v144, v138, v144
	s_waitcnt lgkmcnt(1)
	v_mfma_f32_32x32x16_bf16 v[80:95], v[194:197], v[124:127], v[80:95]
	v_exp_f32_e32 v129, v129
	v_add_f32_e32 v144, v139, v144
	v_add_f32_e32 v144, v134, v144
	v_add_f32_e32 v144, v135, v144
	v_add_f32_e32 v144, v128, v144
	v_add_f32_e32 v175, v129, v144
	v_mov_b32_e32 v176, v175
	s_waitcnt lgkmcnt(0)
	v_mfma_f32_32x32x16_bf16 v[64:79], v[198:201], v[124:127], v[64:79]
	ds_read_b128 v[194:197], v167 offset:49152
	ds_read_b128 v[198:201], v167 offset:57344
	v_permlane32_swap_b32_e32 v175, v176
	s_waitcnt lgkmcnt(1)
	v_mfma_f32_32x32x16_bf16 v[80:95], v[194:197], v[116:119], v[80:95]
	s_waitcnt lgkmcnt(0)
	v_mfma_f32_32x32x16_bf16 v[64:79], v[198:201], v[116:119], v[64:79]
	ds_read_b128 v[194:197], v166 offset:49152
	ds_read_b128 v[198:201], v166 offset:57344
	s_waitcnt lgkmcnt(1)
	v_mfma_f32_32x32x16_bf16 v[80:95], v[194:197], v[104:107], v[80:95]
	s_waitcnt lgkmcnt(0)
	v_mfma_f32_32x32x16_bf16 v[64:79], v[198:201], v[104:107], v[64:79]
	ds_read_b128 v[194:197], v172 offset:49152
	ds_read_b128 v[198:201], v172 offset:57344
	s_waitcnt lgkmcnt(1)
	v_mfma_f32_32x32x16_bf16 v[80:95], v[194:197], v[100:103], v[80:95]
	s_waitcnt lgkmcnt(0)
	v_mfma_f32_32x32x16_bf16 v[64:79], v[198:201], v[100:103], v[64:79]
	ds_read_b128 v[194:197], v171 offset:49152
	ds_read_b128 v[198:201], v171 offset:57344
	v_cvt_pk_bf16_f32 v144, v145, v187
	v_cvt_pk_bf16_f32 v145, v146, v188
	v_cvt_pk_bf16_f32 v146, v186, v189
	v_cvt_pk_bf16_f32 v147, v147, v185
	v_cvt_pk_bf16_f32 v184, v157, v181
	v_cvt_pk_bf16_f32 v185, v179, v182
	s_waitcnt lgkmcnt(1)
	v_mfma_f32_32x32x16_bf16 v[80:95], v[194:197], v[96:99], v[80:95]
	v_permlane32_swap_b32_e32 v144, v146
	v_cvt_pk_bf16_f32 v186, v154, v155
	v_cvt_pk_bf16_f32 v187, v156, v180
	v_cvt_pk_bf16_f32 v180, v142, v143
	v_cvt_pk_bf16_f32 v181, v140, v141
	v_cvt_pk_bf16_f32 v182, v136, v137
	s_waitcnt lgkmcnt(0)
	v_mfma_f32_32x32x16_bf16 v[64:79], v[198:201], v[96:99], v[64:79]
	v_cvt_pk_bf16_f32 v183, v132, v133
	v_cvt_pk_bf16_f32 v188, v130, v131
	v_cvt_pk_bf16_f32 v189, v138, v139
	v_cvt_pk_bf16_f32 v190, v134, v135
	v_cvt_pk_bf16_f32 v191, v128, v129
	v_permlane32_swap_b32_e32 v145, v147
	v_permlane32_swap_b32_e32 v184, v186
	v_permlane32_swap_b32_e32 v185, v187
	v_permlane32_swap_b32_e32 v180, v182
	v_permlane32_swap_b32_e32 v181, v183
	v_permlane32_swap_b32_e32 v188, v190
	v_permlane32_swap_b32_e32 v189, v191
	s_add_u32 s46, s10, s0
	s_addc_u32 s47, s11, 0
	s_add_u32 s48, s10, s67
	s_addc_u32 s49, s11, 0
	global_load_dwordx4 v[128:131], v192, s[46:47]
	global_load_dwordx4 v[132:135], v152, s[46:47]
	global_load_dwordx4 v[136:139], v192, s[48:49]
	global_load_dwordx4 v[140:143], v152, s[48:49]
	ds_read_b64_tr_b16 v[194:195], v160 offset:0
	ds_read_b64_tr_b16 v[196:197], v160 offset:0x800
	ds_read_b64_tr_b16 v[198:199], v160 offset:0x1000
	ds_read_b64_tr_b16 v[200:201], v160 offset:0x1800
	ds_read_b64_tr_b16 v[202:203], v160 offset:0x2000
	ds_read_b64_tr_b16 v[204:205], v160 offset:0x2800
	ds_read_b64_tr_b16 v[206:207], v160 offset:0x3000
	ds_read_b64_tr_b16 v[208:209], v160 offset:0x3800
	s_waitcnt lgkmcnt(0)
	v_mfma_f32_32x32x16_bf16 v[0:15], v[144:147], v[194:197], v[0:15]
	ds_read_b64_tr_b16 v[194:195], v160 offset:0x200
	ds_read_b64_tr_b16 v[196:197], v160 offset:0xa00
	v_mfma_f32_32x32x16_bf16 v[0:15], v[184:187], v[198:201], v[0:15]
	ds_read_b64_tr_b16 v[198:199], v160 offset:0x1200
	ds_read_b64_tr_b16 v[200:201], v160 offset:0x1a00
	v_mfma_f32_32x32x16_bf16 v[0:15], v[180:183], v[202:205], v[0:15]
	ds_read_b64_tr_b16 v[202:203], v160 offset:0x2200
	ds_read_b64_tr_b16 v[204:205], v160 offset:0x2a00
	v_mfma_f32_32x32x16_bf16 v[0:15], v[188:191], v[206:209], v[0:15]
	ds_read_b64_tr_b16 v[206:207], v160 offset:0x3200
	ds_read_b64_tr_b16 v[208:209], v160 offset:0x3a00
	s_waitcnt lgkmcnt(0)
; #define SBAR() __builtin_amdgcn_sched_barrier(0)
; template <int DK>
; __device__ __forceinline__ void partialSM(f32x16& p0, f32x16& p1, float& m_reg, float& mn, float& alpha) {
;   constexpr float SCALE = Cst<DK>::SCALE, C = SCALE * 1.4426950408889634f;
;   float pmax = p0[0];
; #pragma unroll
;   for (int r = 1; r < 16; ++r) pmax = fmaxf(pmax, p0[r]);
; #pragma unroll
;   for (int r = 0; r < 16; ++r) pmax = fmaxf(pmax, p1[r]);
;   { auto rr = __builtin_amdgcn_permlane32_swap(__float_as_uint(pmax), __float_as_uint(pmax), false, false);
;     pmax = fmaxf(__uint_as_float(rr[0]), __uint_as_float(rr[1])); }
;   if (__builtin_expect(__all(pmax - m_reg <= THR / SCALE), 1)) { mn = m_reg; alpha = 1.f; }
;   else { mn = fmaxf(m_reg, pmax); alpha = __builtin_amdgcn_exp2f((m_reg - mn) * C); m_reg = mn; }
; template <int D0> __device__ __forceinline__ void pv_one(f32x16& od, int vb, bf16x8 pa0, bf16x8 pa1, bf16x8 pa2, bf16x8 pa3) {
;   const s16x4 l0 = tr_read<v_rd_off(D0, 0, 0)>(vb), h0 = tr_read<v_rd_off(D0, 0, 1)>(vb), l1 = tr_read<v_rd_off(D0, 1, 0)>(vb), h1 = tr_read<v_rd_off(D0, 1, 1)>(vb);
;   const s16x4 l2 = tr_read<v_rd_off(D0, 2, 0)>(vb), h2 = tr_read<v_rd_off(D0, 2, 1)>(vb), l3 = tr_read<v_rd_off(D0, 3, 0)>(vb), h3 = tr_read<v_rd_off(D0, 3, 1)>(vb);
;   asm volatile("s_waitcnt lgkmcnt(0)" ::: "memory"); SBAR();
;     ...
;   od = __builtin_amdgcn_mfma_f32_32x32x16_bf16(pa0, PK(l0, h0), od, 0, 0, 0);
;   od = __builtin_amdgcn_mfma_f32_32x32x16_bf16(pa1, PK(l1, h1), od, 0, 0, 0);
;   od = __builtin_amdgcn_mfma_f32_32x32x16_bf16(pa2, PK(l2, h2), od, 0, 0, 0);
;   od = __builtin_amdgcn_mfma_f32_32x32x16_bf16(pa3, PK(l3, h3), od, 0, 0, 0);
;     ...
; }
; __device__ __forceinline__ void pv_d0(f32x16* o, int vb, bf16x8 pa0, bf16x8 pa1, bf16x8 pa2, bf16x8 pa3) {
;   pv_one<0>(o[0], vb, pa0, pa1, pa2, pa3); pv_one<1>(o[1], vb, pa0, pa1, pa2, pa3); pv_one<2>(o[2], vb, pa0, pa1, pa2, pa3); pv_one<3>(o[3], vb, pa0, pa1, pa2, pa3);
; }
; template <int DK, int LDQ, int LDK, int LDV, int LDO, int SDEPTH, int NPARK>
; __device__ __forceinline__ void body(const bf16_t* __restrict__ Qb, const bf16_t* __restrict__ Kh, const bf16_t* __restrict__ Vh, bf16_t* __restrict__ Ob, int seq, char* lds, int tid, int wid) {
;   constexpr int SHM_K = KVBLK * DK * 2, ND0 = DK / 16;
;   const int lane = tid & 63, r32 = lane & 31, hi = lane >> 5;
;   char* V_lds = lds; char* K_lds = lds + 2 * SHM_V;
	v_mfma_f32_32x32x16_bf16 v[48:63], v[144:147], v[194:197], v[48:63]
	ds_read_b64_tr_b16 v[194:195], v160 offset:0x400
	ds_read_b64_tr_b16 v[196:197], v160 offset:0xc00
	v_mfma_f32_32x32x16_bf16 v[48:63], v[184:187], v[198:201], v[48:63]
	ds_read_b64_tr_b16 v[198:199], v160 offset:0x1400
	ds_read_b64_tr_b16 v[200:201], v160 offset:0x1c00
	v_mfma_f32_32x32x16_bf16 v[48:63], v[180:183], v[202:205], v[48:63]
	ds_read_b64_tr_b16 v[202:203], v160 offset:0x2400
	ds_read_b64_tr_b16 v[204:205], v160 offset:0x2c00
	v_mfma_f32_32x32x16_bf16 v[48:63], v[188:191], v[206:209], v[48:63]
	ds_read_b64_tr_b16 v[206:207], v160 offset:0x3400
	ds_read_b64_tr_b16 v[208:209], v160 offset:0x3c00
	s_waitcnt lgkmcnt(0)
	v_mfma_f32_32x32x16_bf16 v[32:47], v[144:147], v[194:197], v[32:47]
	ds_read_b64_tr_b16 v[194:195], v160 offset:0x600
	ds_read_b64_tr_b16 v[196:197], v160 offset:0xe00
	v_mfma_f32_32x32x16_bf16 v[32:47], v[184:187], v[198:201], v[32:47]
	ds_read_b64_tr_b16 v[198:199], v160 offset:0x1600
	ds_read_b64_tr_b16 v[200:201], v160 offset:0x1e00
	v_mfma_f32_32x32x16_bf16 v[32:47], v[180:183], v[202:205], v[32:47]
	ds_read_b64_tr_b16 v[202:203], v160 offset:0x2600
	ds_read_b64_tr_b16 v[204:205], v160 offset:0x2e00
	v_mfma_f32_32x32x16_bf16 v[32:47], v[188:191], v[206:209], v[32:47]
	ds_read_b64_tr_b16 v[206:207], v160 offset:0x3600
	ds_read_b64_tr_b16 v[208:209], v160 offset:0x3e00
	s_waitcnt lgkmcnt(0)
	v_mfma_f32_32x32x16_bf16 v[16:31], v[144:147], v[194:197], v[16:31]
	v_max_f32_e32 v144, v80, v81
	v_max3_f32 v144, v144, v82, v83
	v_max3_f32 v144, v144, v84, v85
	v_max3_f32 v144, v144, v86, v87
	v_max3_f32 v144, v144, v88, v89
	v_max3_f32 v144, v144, v90, v91
	v_max3_f32 v144, v144, v92, v93
	v_mfma_f32_32x32x16_bf16 v[16:31], v[184:187], v[198:201], v[16:31]
	v_max3_f32 v144, v144, v94, v95
	v_max3_f32 v144, v144, v64, v65
	v_max3_f32 v144, v144, v66, v67
	v_max3_f32 v144, v144, v68, v69
	v_max3_f32 v144, v144, v70, v71
	v_max3_f32 v144, v144, v72, v73
	v_max3_f32 v144, v144, v74, v75
	v_max3_f32 v144, v144, v76, v77
	v_mfma_f32_32x32x16_bf16 v[16:31], v[180:183], v[202:205], v[16:31]
	v_max3_f32 v144, v144, v78, v79
	v_mov_b32_e32 v145, v144
	s_nop 1
	v_permlane32_swap_b32_e32 v144, v145
	v_max_f32_e32 v144, v144, v145
	v_sub_f32_e32 v145, v144, v174
	v_cmp_ge_f32_e32 vcc, s1, v145
	v_max_f32_e32 v144, v174, v144
	v_mfma_f32_32x32x16_bf16 v[16:31], v[188:191], v[206:209], v[16:31]
	v_sub_f32_e32 v145, v174, v144
	v_mul_f32_e32 v145, 0x3e0293ee, v145
	v_exp_f32_e32 v145, v145
	s_cmp_eq_u64 vcc, exec
	s_cselect_b64 s[8:9], -1, 0
	s_barrier
	s_waitcnt vmcnt(0)
	v_cndmask_b32_e64 v177, v145, 1.0, s[8:9]
	v_cmp_gt_f32_e32 vcc, 1.0, v177
	ds_write_b128 v164, v[128:131]
	ds_write_b128 v165, v[132:135]
	ds_write_b128 v162, v[136:139] offset:32768
	ds_write_b128 v163, v[140:143] offset:32768
	s_cbranch_vccz .LBB0_928
	s_and_saveexec_b64 s[12:13], s[6:7]
	ds_write_b32 v151, v177 offset:128
	s_or_b64 exec, exec, s[12:13]
	s_waitcnt lgkmcnt(0)
	v_add_u32_e32 v140, s95, v150
	ds_read_b128 v[128:131], v140 offset:224
	ds_read_b128 v[132:135], v140 offset:192
	ds_read_b128 v[136:139], v140 offset:160
	ds_read_b128 v[140:143], v140 offset:128
	s_waitcnt lgkmcnt(3)
	v_pk_mul_f32 v[12:13], v[12:13], v[128:129]
	s_waitcnt lgkmcnt(2)
	v_pk_mul_f32 v[8:9], v[8:9], v[132:133]
	s_waitcnt lgkmcnt(1)
	v_pk_mul_f32 v[4:5], v[4:5], v[136:137]
	v_pk_mul_f32 v[14:15], v[14:15], v[130:131]
	v_pk_mul_f32 v[10:11], v[10:11], v[134:135]
	v_pk_mul_f32 v[6:7], v[6:7], v[138:139]
	s_waitcnt lgkmcnt(0)
	v_pk_mul_f32 v[2:3], v[2:3], v[142:143]
	v_pk_mul_f32 v[0:1], v[0:1], v[140:141]
	v_pk_mul_f32 v[60:61], v[60:61], v[128:129]
	v_pk_mul_f32 v[56:57], v[56:57], v[132:133]
	v_pk_mul_f32 v[52:53], v[52:53], v[136:137]
	v_pk_mul_f32 v[62:63], v[62:63], v[130:131]
	v_pk_mul_f32 v[58:59], v[58:59], v[134:135]
	v_pk_mul_f32 v[54:55], v[54:55], v[138:139]
	v_pk_mul_f32 v[50:51], v[50:51], v[142:143]
	v_pk_mul_f32 v[48:49], v[48:49], v[140:141]
	v_pk_mul_f32 v[44:45], v[44:45], v[128:129]
	v_pk_mul_f32 v[40:41], v[40:41], v[132:133]
	v_pk_mul_f32 v[36:37], v[36:37], v[136:137]
	v_pk_mul_f32 v[46:47], v[46:47], v[130:131]
	v_pk_mul_f32 v[42:43], v[42:43], v[134:135]
	v_pk_mul_f32 v[38:39], v[38:39], v[138:139]
	v_pk_mul_f32 v[34:35], v[34:35], v[142:143]
	v_pk_mul_f32 v[32:33], v[32:33], v[140:141]
	v_pk_mul_f32 v[28:29], v[28:29], v[128:129]
	v_pk_mul_f32 v[24:25], v[24:25], v[132:133]
	v_pk_mul_f32 v[20:21], v[20:21], v[136:137]
	v_pk_mul_f32 v[30:31], v[30:31], v[130:131]
	v_pk_mul_f32 v[26:27], v[26:27], v[134:135]
	v_pk_mul_f32 v[22:23], v[22:23], v[138:139]
	v_pk_mul_f32 v[18:19], v[18:19], v[142:143]
	v_pk_mul_f32 v[16:17], v[16:17], v[140:141]
; template <int DK>
; __device__ __forceinline__ void partialSM(f32x16& p0, f32x16& p1, float& m_reg, float& mn, float& alpha) {
;     ...
;   float mnC = -mn * C;
; #pragma unroll
;   for (int r = 0; r < 16; ++r) p0[r] = fmaf(p0[r], C, mnC);
; #pragma unroll
;   for (int r = 0; r < 16; ++r) p1[r] = fmaf(p1[r], C, mnC);
; #pragma unroll
;   for (int r = 0; r < 16; ++r) p0[r] = __builtin_amdgcn_exp2f(p0[r]);
; }
; __device__ __forceinline__ void finishSM(f32x16& p0, f32x16& p1, float alpha, float& l_reg, bf16x8& pa0, bf16x8& pa1, bf16x8& pa2, bf16x8& pa3) {
; #pragma unroll
;   for (int r = 0; r < 16; ++r) p1[r] = __builtin_amdgcn_exp2f(p1[r]);
;   float ps = 0;
; #pragma unroll
;   for (int r = 0; r < 16; ++r) ps += p0[r];
; #pragma unroll
;   for (int r = 0; r < 16; ++r) ps += p1[r];
;   { auto rr = __builtin_amdgcn_permlane32_swap(__float_as_uint(ps), __float_as_uint(ps), false, false);
;     ps = __uint_as_float(rr[0]) + __uint_as_float(rr[1]); }
;   l_reg = l_reg * alpha + ps;
;     ...
;   PK4(p0, 0, pa0); PK4(p0, 8, pa1); PK4(p1, 0, pa2); PK4(p1, 8, pa3);
;     ...
; }
; template <int DK, int NPARK>
; __device__ __forceinline__ void qkt(f32x16& p0, f32x16& p1, const char* Ks, const bf16x8* qr, const char* qpark, int r32, int hi) {
;   p0 = f32x16{}; p1 = f32x16{};
; #pragma unroll
;   for (int d0 = 0; d0 < DK / 16; ++d0) { const int cb = (d0 * 16 + hi * 8) * 2;
;     bf16x8 b0 = *reinterpret_cast<const bf16x8*>(Ks + kswz<DK>(r32, cb));
;     bf16x8 b1 = *reinterpret_cast<const bf16x8*>(Ks + kswz<DK>(32 + r32, cb));
;     bf16x8 q;
;     if constexpr (NPARK > 0) { if (d0 >= DK / 16 - NPARK) q = *reinterpret_cast<const bf16x8*>(qpark + (d0 - (DK / 16 - NPARK)) * 1024); else q = qr[d0]; } else q = qr[d0];
;     p0 = __builtin_amdgcn_mfma_f32_32x32x16_bf16(b0, q, p0, 0, 0, 0);
;     p1 = __builtin_amdgcn_mfma_f32_32x32x16_bf16(b1, q, p1, 0, 0, 0); }
.LBB0_928:
	v_cndmask_b32_e64 v174, v144, v174, s[8:9]
	v_mul_f32_e32 v144, 0xbe0293ee, v174
	v_pk_fma_f32 v[80:81], v[80:81], s[76:77], v[144:145] op_sel_hi:[1,0,0]
	v_pk_fma_f32 v[82:83], v[82:83], s[76:77], v[144:145] op_sel_hi:[1,0,0]
	v_pk_fma_f32 v[84:85], v[84:85], s[76:77], v[144:145] op_sel_hi:[1,0,0]
	v_pk_fma_f32 v[86:87], v[86:87], s[76:77], v[144:145] op_sel_hi:[1,0,0]
	v_pk_fma_f32 v[88:89], v[88:89], s[76:77], v[144:145] op_sel_hi:[1,0,0]
	v_pk_fma_f32 v[90:91], v[90:91], s[76:77], v[144:145] op_sel_hi:[1,0,0]
	v_pk_fma_f32 v[92:93], v[92:93], s[76:77], v[144:145] op_sel_hi:[1,0,0]
	v_pk_fma_f32 v[94:95], v[94:95], s[76:77], v[144:145] op_sel_hi:[1,0,0]
	v_fmamk_f32 v184, v64, 0x3e0293ee, v144
	v_fmamk_f32 v185, v65, 0x3e0293ee, v144
	v_fmamk_f32 v186, v66, 0x3e0293ee, v144
	v_fmamk_f32 v187, v67, 0x3e0293ee, v144
	v_fmamk_f32 v188, v68, 0x3e0293ee, v144
	v_fmamk_f32 v146, v69, 0x3e0293ee, v144
	v_fmamk_f32 v147, v70, 0x3e0293ee, v144
	v_fmamk_f32 v179, v71, 0x3e0293ee, v144
	v_fmamk_f32 v180, v72, 0x3e0293ee, v144
	v_fmamk_f32 v181, v73, 0x3e0293ee, v144
	v_fmamk_f32 v182, v74, 0x3e0293ee, v144
	v_fmamk_f32 v183, v75, 0x3e0293ee, v144
	v_fmamk_f32 v145, v76, 0x3e0293ee, v144
	v_fmamk_f32 v189, v77, 0x3e0293ee, v144
	v_fmamk_f32 v190, v78, 0x3e0293ee, v144
	v_fmac_f32_e32 v144, 0x3e0293ee, v79
	v_exp_f32_e32 v141, v80
	v_exp_f32_e32 v143, v81
	v_exp_f32_e32 v139, v82
	v_exp_f32_e32 v142, v83
	v_exp_f32_e32 v138, v84
	v_exp_f32_e32 v140, v85
	v_exp_f32_e32 v136, v86
	v_exp_f32_e32 v137, v87
	v_exp_f32_e32 v133, v88
	v_exp_f32_e32 v135, v89
	v_exp_f32_e32 v132, v90
	v_exp_f32_e32 v134, v91
	v_exp_f32_e32 v129, v92
	v_exp_f32_e32 v131, v93
	v_exp_f32_e32 v128, v94
	v_exp_f32_e32 v130, v95
	s_waitcnt lgkmcnt(0)
	s_barrier
	ds_read_b128 v[64:67], v161 offset:32768
	ds_read_b128 v[68:71], v161 offset:40960
	ds_read_b128 v[194:197], v170 offset:32768
	ds_read_b128 v[198:201], v170 offset:40960
	v_exp_f32_e32 v203, v144
	s_waitcnt lgkmcnt(3)
	v_mfma_f32_32x32x16_bf16 v[80:95], v[64:67], v[112:115], 0
	v_add_f32_e32 v144, v143, v141
	v_add_f32_e32 v144, v139, v144
	v_add_f32_e32 v144, v142, v144
	v_add_f32_e32 v144, v138, v144
	v_add_f32_e32 v144, v140, v144
	v_add_f32_e32 v144, v136, v144
	v_add_f32_e32 v144, v137, v144
	s_waitcnt lgkmcnt(2)
	v_mfma_f32_32x32x16_bf16 v[64:79], v[68:71], v[112:115], 0
	v_add_f32_e32 v144, v133, v144
	v_add_f32_e32 v144, v135, v144
	v_add_f32_e32 v144, v132, v144
	v_add_f32_e32 v144, v134, v144
	v_exp_f32_e32 v191, v184
	v_add_f32_e32 v144, v129, v144
	v_exp_f32_e32 v185, v185
	s_waitcnt lgkmcnt(1)
	v_mfma_f32_32x32x16_bf16 v[80:95], v[194:197], v[108:111], v[80:95]
	v_add_f32_e32 v144, v131, v144
	v_add_f32_e32 v144, v128, v144
	v_add_f32_e32 v144, v130, v144
	v_add_f32_e32 v144, v191, v144
	v_add_f32_e32 v144, v185, v144
	v_exp_f32_e32 v179, v179
	v_exp_f32_e32 v180, v180
	s_waitcnt lgkmcnt(0)
	v_mfma_f32_32x32x16_bf16 v[64:79], v[198:201], v[108:111], v[64:79]
	ds_read_b128 v[194:197], v169 offset:32768
	ds_read_b128 v[198:201], v169 offset:40960
	v_exp_f32_e32 v181, v181
	v_exp_f32_e32 v182, v182
	v_exp_f32_e32 v202, v189
	v_exp_f32_e32 v190, v190
	s_waitcnt lgkmcnt(1)
	v_mfma_f32_32x32x16_bf16 v[80:95], v[194:197], v[120:123], v[80:95]
	s_waitcnt lgkmcnt(0)
	v_mfma_f32_32x32x16_bf16 v[64:79], v[198:201], v[120:123], v[64:79]
	ds_read_b128 v[194:197], v168 offset:32768
	ds_read_b128 v[198:201], v168 offset:40960
	s_waitcnt lgkmcnt(1)
	v_mfma_f32_32x32x16_bf16 v[80:95], v[194:197], v[124:127], v[80:95]
	s_waitcnt lgkmcnt(0)
	v_mfma_f32_32x32x16_bf16 v[64:79], v[198:201], v[124:127], v[64:79]
	ds_read_b128 v[194:197], v167 offset:32768
	ds_read_b128 v[198:201], v167 offset:40960
	s_waitcnt lgkmcnt(1)
	v_mfma_f32_32x32x16_bf16 v[80:95], v[194:197], v[116:119], v[80:95]
	s_waitcnt lgkmcnt(0)
	v_mfma_f32_32x32x16_bf16 v[64:79], v[198:201], v[116:119], v[64:79]
	ds_read_b128 v[194:197], v166 offset:32768
	ds_read_b128 v[198:201], v166 offset:40960
	s_waitcnt lgkmcnt(1)
	v_mfma_f32_32x32x16_bf16 v[80:95], v[194:197], v[104:107], v[80:95]
	s_waitcnt lgkmcnt(0)
	v_mfma_f32_32x32x16_bf16 v[64:79], v[198:201], v[104:107], v[64:79]
	ds_read_b128 v[194:197], v172 offset:32768
	ds_read_b128 v[198:201], v172 offset:40960
	s_waitcnt lgkmcnt(1)
	v_mfma_f32_32x32x16_bf16 v[80:95], v[194:197], v[100:103], v[80:95]
	s_waitcnt lgkmcnt(0)
	v_mfma_f32_32x32x16_bf16 v[64:79], v[198:201], v[100:103], v[64:79]
	ds_read_b128 v[194:197], v171 offset:32768
	ds_read_b128 v[198:201], v171 offset:40960
	s_waitcnt lgkmcnt(1)
	v_mfma_f32_32x32x16_bf16 v[80:95], v[194:197], v[96:99], v[80:95]
	v_exp_f32_e32 v195, v186
	v_exp_f32_e32 v196, v187
	v_exp_f32_e32 v197, v188
	v_add_f32_e32 v144, v195, v144
	v_add_f32_e32 v144, v196, v144
	v_add_f32_e32 v144, v197, v144
	s_waitcnt lgkmcnt(0)
; #define SBAR() __builtin_amdgcn_sched_barrier(0)
; __device__ __forceinline__ void finishSM(f32x16& p0, f32x16& p1, float alpha, float& l_reg, bf16x8& pa0, bf16x8& pa1, bf16x8& pa2, bf16x8& pa3) {
; #pragma unroll
;   for (int r = 0; r < 16; ++r) p1[r] = __builtin_amdgcn_exp2f(p1[r]);
;   float ps = 0;
; #pragma unroll
;   for (int r = 0; r < 16; ++r) ps += p0[r];
; #pragma unroll
;   for (int r = 0; r < 16; ++r) ps += p1[r];
;   { auto rr = __builtin_amdgcn_permlane32_swap(__float_as_uint(ps), __float_as_uint(ps), false, false);
;     ps = __uint_as_float(rr[0]) + __uint_as_float(rr[1]); }
;   l_reg = l_reg * alpha + ps;
;     ...
;   PK4(p0, 0, pa0); PK4(p0, 8, pa1); PK4(p1, 0, pa2); PK4(p1, 8, pa3);
;     ...
; }
; template <int OFF> __device__ __forceinline__ s16x4 tr_read(int vb) {
;   s16x4 r; asm volatile("ds_read_b64_tr_b16 %0, %1 offset:%2" : "=&v"(r) : "v"(vb), "i"(OFF) : "memory"); return r;
; }
; template <int D0> __device__ __forceinline__ void pv_one(f32x16& od, int vb, bf16x8 pa0, bf16x8 pa1, bf16x8 pa2, bf16x8 pa3) {
;   const s16x4 l0 = tr_read<v_rd_off(D0, 0, 0)>(vb), h0 = tr_read<v_rd_off(D0, 0, 1)>(vb), l1 = tr_read<v_rd_off(D0, 1, 0)>(vb), h1 = tr_read<v_rd_off(D0, 1, 1)>(vb);
;   const s16x4 l2 = tr_read<v_rd_off(D0, 2, 0)>(vb), h2 = tr_read<v_rd_off(D0, 2, 1)>(vb), l3 = tr_read<v_rd_off(D0, 3, 0)>(vb), h3 = tr_read<v_rd_off(D0, 3, 1)>(vb);
;   asm volatile("s_waitcnt lgkmcnt(0)" ::: "memory"); SBAR();
;     ...
;   od = __builtin_amdgcn_mfma_f32_32x32x16_bf16(pa0, PK(l0, h0), od, 0, 0, 0);
;   od = __builtin_amdgcn_mfma_f32_32x32x16_bf16(pa1, PK(l1, h1), od, 0, 0, 0);
;   od = __builtin_amdgcn_mfma_f32_32x32x16_bf16(pa2, PK(l2, h2), od, 0, 0, 0);
;   od = __builtin_amdgcn_mfma_f32_32x32x16_bf16(pa3, PK(l3, h3), od, 0, 0, 0);
;     ...
; }
	v_mfma_f32_32x32x16_bf16 v[64:79], v[198:201], v[96:99], v[64:79]
	v_exp_f32_e32 v198, v146
	v_exp_f32_e32 v199, v147
	v_exp_f32_e32 v200, v183
	v_exp_f32_e32 v201, v145
	v_add_f32_e32 v144, v198, v144
	v_add_f32_e32 v144, v199, v144
	v_add_f32_e32 v144, v179, v144
	v_add_f32_e32 v144, v180, v144
	v_add_f32_e32 v144, v181, v144
	v_add_f32_e32 v144, v182, v144
	v_add_f32_e32 v144, v200, v144
	v_add_f32_e32 v144, v201, v144
	v_add_f32_e32 v144, v202, v144
	v_add_f32_e32 v144, v190, v144
	v_add_f32_e32 v183, v203, v144
	v_mov_b32_e32 v184, v183
	v_cvt_pk_bf16_f32 v144, v141, v143
	v_cvt_pk_bf16_f32 v145, v139, v142
	v_cvt_pk_bf16_f32 v146, v138, v140
	v_cvt_pk_bf16_f32 v147, v136, v137
	s_nop 1
	v_permlane32_swap_b32_e32 v183, v184
	v_permlane32_swap_b32_e32 v144, v146
	v_permlane32_swap_b32_e32 v145, v147
	v_cvt_pk_bf16_f32 v186, v133, v135
	v_cvt_pk_bf16_f32 v187, v132, v134
	v_cvt_pk_bf16_f32 v188, v129, v131
	v_cvt_pk_bf16_f32 v189, v128, v130
	v_cvt_pk_bf16_f32 v194, v191, v185
	v_cvt_pk_bf16_f32 v195, v195, v196
	v_cvt_pk_bf16_f32 v196, v197, v198
	v_cvt_pk_bf16_f32 v197, v199, v179
	v_cvt_pk_bf16_f32 v198, v180, v181
	v_cvt_pk_bf16_f32 v199, v182, v200
	v_cvt_pk_bf16_f32 v200, v201, v202
	v_cvt_pk_bf16_f32 v201, v190, v203
	s_nop 0
	v_permlane32_swap_b32_e32 v186, v188
	v_permlane32_swap_b32_e32 v187, v189
	v_permlane32_swap_b32_e32 v194, v196
	v_permlane32_swap_b32_e32 v195, v197
	v_permlane32_swap_b32_e32 v198, v200
	v_permlane32_swap_b32_e32 v199, v201
	s_add_u32 s46, s10, s61
	s_addc_u32 s47, s11, 0
	s_add_u32 s48, s10, s64
	s_addc_u32 s49, s11, 0
	global_load_dwordx4 v[128:131], v192, s[46:47]
	global_load_dwordx4 v[132:135], v152, s[46:47]
	global_load_dwordx4 v[136:139], v192, s[48:49]
	global_load_dwordx4 v[140:143], v152, s[48:49]
	ds_read_b64_tr_b16 v[154:155], v159 offset:0
	ds_read_b64_tr_b16 v[156:157], v159 offset:0x800
	ds_read_b64_tr_b16 v[202:203], v159 offset:0x1000
	ds_read_b64_tr_b16 v[204:205], v159 offset:0x1800
	ds_read_b64_tr_b16 v[206:207], v159 offset:0x2000
	ds_read_b64_tr_b16 v[208:209], v159 offset:0x2800
	ds_read_b64_tr_b16 v[210:211], v159 offset:0x3000
	ds_read_b64_tr_b16 v[212:213], v159 offset:0x3800
	s_waitcnt lgkmcnt(0)
	v_mfma_f32_32x32x16_bf16 v[0:15], v[144:147], v[154:157], v[0:15]
	ds_read_b64_tr_b16 v[154:155], v159 offset:0x200
	ds_read_b64_tr_b16 v[156:157], v159 offset:0xa00
	v_mfma_f32_32x32x16_bf16 v[0:15], v[186:189], v[202:205], v[0:15]
	ds_read_b64_tr_b16 v[202:203], v159 offset:0x1200
	ds_read_b64_tr_b16 v[204:205], v159 offset:0x1a00
	v_mfma_f32_32x32x16_bf16 v[0:15], v[194:197], v[206:209], v[0:15]
	ds_read_b64_tr_b16 v[206:207], v159 offset:0x2200
	ds_read_b64_tr_b16 v[208:209], v159 offset:0x2a00
	v_mfma_f32_32x32x16_bf16 v[0:15], v[198:201], v[210:213], v[0:15]
	ds_read_b64_tr_b16 v[210:211], v159 offset:0x3200
	ds_read_b64_tr_b16 v[212:213], v159 offset:0x3a00
	s_waitcnt lgkmcnt(0)
	v_mfma_f32_32x32x16_bf16 v[48:63], v[144:147], v[154:157], v[48:63]
	ds_read_b64_tr_b16 v[154:155], v159 offset:0x400
	ds_read_b64_tr_b16 v[156:157], v159 offset:0xc00
	v_mfma_f32_32x32x16_bf16 v[48:63], v[186:189], v[202:205], v[48:63]
	ds_read_b64_tr_b16 v[202:203], v159 offset:0x1400
	ds_read_b64_tr_b16 v[204:205], v159 offset:0x1c00
	v_mfma_f32_32x32x16_bf16 v[48:63], v[194:197], v[206:209], v[48:63]
	ds_read_b64_tr_b16 v[206:207], v159 offset:0x2400
	ds_read_b64_tr_b16 v[208:209], v159 offset:0x2c00
	v_mfma_f32_32x32x16_bf16 v[48:63], v[198:201], v[210:213], v[48:63]
	ds_read_b64_tr_b16 v[210:211], v159 offset:0x3400
	ds_read_b64_tr_b16 v[212:213], v159 offset:0x3c00
	s_waitcnt lgkmcnt(0)
	v_mfma_f32_32x32x16_bf16 v[32:47], v[144:147], v[154:157], v[32:47]
	ds_read_b64_tr_b16 v[154:155], v159 offset:0x600
	ds_read_b64_tr_b16 v[156:157], v159 offset:0xe00
	v_mfma_f32_32x32x16_bf16 v[32:47], v[186:189], v[202:205], v[32:47]
	ds_read_b64_tr_b16 v[202:203], v159 offset:0x1600
	ds_read_b64_tr_b16 v[204:205], v159 offset:0x1e00
	v_mfma_f32_32x32x16_bf16 v[32:47], v[194:197], v[206:209], v[32:47]
	ds_read_b64_tr_b16 v[206:207], v159 offset:0x2600
	ds_read_b64_tr_b16 v[208:209], v159 offset:0x2e00
	v_mfma_f32_32x32x16_bf16 v[32:47], v[198:201], v[210:213], v[32:47]
	ds_read_b64_tr_b16 v[210:211], v159 offset:0x3600
	ds_read_b64_tr_b16 v[212:213], v159 offset:0x3e00
	s_waitcnt lgkmcnt(0)
	v_mfma_f32_32x32x16_bf16 v[16:31], v[144:147], v[154:157], v[16:31]
	v_max_f32_e32 v144, v80, v81
	v_max3_f32 v144, v144, v82, v83
	v_max3_f32 v144, v144, v84, v85
	v_max3_f32 v144, v144, v86, v87
	v_max3_f32 v144, v144, v88, v89
	v_max3_f32 v144, v144, v90, v91
	v_max3_f32 v144, v144, v92, v93
	v_mfma_f32_32x32x16_bf16 v[16:31], v[186:189], v[202:205], v[16:31]
	v_max3_f32 v144, v144, v94, v95
	v_max3_f32 v144, v144, v64, v65
	v_max3_f32 v144, v144, v66, v67
	v_max3_f32 v144, v144, v68, v69
	v_max3_f32 v144, v144, v70, v71
	v_max3_f32 v144, v144, v72, v73
	v_max3_f32 v144, v144, v74, v75
	v_max3_f32 v144, v144, v76, v77
	v_mfma_f32_32x32x16_bf16 v[16:31], v[194:197], v[206:209], v[16:31]
	v_max3_f32 v144, v144, v78, v79
	v_mov_b32_e32 v145, v144
	s_nop 1
	v_permlane32_swap_b32_e32 v144, v145
	v_max_f32_e32 v144, v144, v145
	v_sub_f32_e32 v145, v144, v174
	v_cmp_ge_f32_e32 vcc, s1, v145
	v_max_f32_e32 v145, v174, v144
	v_mfma_f32_32x32x16_bf16 v[16:31], v[198:201], v[210:213], v[16:31]
	v_sub_f32_e32 v144, v174, v145
	v_mul_f32_e32 v144, 0x3e0293ee, v144
	v_exp_f32_e32 v144, v144
	s_cmp_eq_u64 vcc, exec
	s_cselect_b64 s[8:9], -1, 0
	s_barrier
; #define SBAR() __builtin_amdgcn_sched_barrier(0)
; template <int DK>
; __device__ __forceinline__ void partialSM(f32x16& p0, f32x16& p1, float& m_reg, float& mn, float& alpha) {
;     ...
;   if (__builtin_expect(__all(pmax - m_reg <= THR / SCALE), 1)) { mn = m_reg; alpha = 1.f; }
;   else { mn = fmaxf(m_reg, pmax); alpha = __builtin_amdgcn_exp2f((m_reg - mn) * C); m_reg = mn; }
;   float mnC = -mn * C;
; #pragma unroll
;   for (int r = 0; r < 16; ++r) p0[r] = fmaf(p0[r], C, mnC);
; #pragma unroll
;   for (int r = 0; r < 16; ++r) p1[r] = fmaf(p1[r], C, mnC);
; #pragma unroll
;   for (int r = 0; r < 16; ++r) p0[r] = __builtin_amdgcn_exp2f(p0[r]);
; template <int DK, int LDQ, int LDK, int LDV, int LDO, int SDEPTH, int NPARK>
; __device__ __forceinline__ void body(const bf16_t* __restrict__ Qb, const bf16_t* __restrict__ Kh, const bf16_t* __restrict__ Vh, bf16_t* __restrict__ Ob, int seq, char* lds, int tid, int wid) {
;     ...
;   f32x16 pA0, pA1, pB0, pB1; float mnA, mnB, alA, alB; bf16x8 pa0, pa1, pa2, pa3; const int NT = seq / KVBLK;
;   constexpr int SE = 0, SO = SDEPTH - 1;
;   SLOAD(SE, 0); asm volatile("s_waitcnt vmcnt(0)" ::: "memory"); SWRITE(0, SE); __syncthreads();
;   qkt<DK, NPARK>(pA0, pA1, K_lds, qr, qpark, r32, hi); partialSM<DK>(pA0, pA1, m_reg, mnA, alA);
;   SLOAD(SO, KVBLK); if constexpr (SDEPTH == 2) { if (2 < NT) SLOAD(SE, 2 * KVBLK); }
;   SWAIT(); SWRITE(1, SO); __syncthreads();
;   for (int j = 1; j + 1 < NT; j += 2) {
;     SBAR(); qkt<DK, NPARK>(pB0, pB1, K_lds + SHM_K, qr, qpark, r32, hi);
;     finishSM(pA0, pA1, alA, l_reg, pa0, pa1, pa2, pa3); SBAR();
;     SLOAD(SO, (j + SDEPTH) * KVBLK); SBAR();
;     pv_d0(o, vb0, pa0, pa1, pa2, pa3); partialSM<DK>(pB0, pB1, m_reg, mnB, alB);
;     __syncthreads(); SWAIT(); SWRITE(0, SE);
;     RESC(alB); __syncthreads();
;     SBAR(); qkt<DK, NPARK>(pA0, pA1, K_lds, qr, qpark, r32, hi);
;     finishSM(pB0, pB1, alB, l_reg, pa0, pa1, pa2, pa3); SBAR();
;     if (SDEPTH == 1 || j + 3 < NT) SLOAD(SE, (j + 1 + SDEPTH) * KVBLK); SBAR();
;     pv_d0(o, vb0 + (int)SHM_V, pa0, pa1, pa2, pa3); partialSM<DK>(pA0, pA1, m_reg, mnA, alA);
;     __syncthreads(); SWAIT(); SWRITE(1, SO);
;     RESC(alA); __syncthreads();
	s_waitcnt vmcnt(0)
	v_cndmask_b32_e64 v144, v144, 1.0, s[8:9]
	v_cmp_gt_f32_e32 vcc, 1.0, v144
	ds_write_b128 v164, v[128:131] offset:16384
	ds_write_b128 v165, v[132:135] offset:16384
	ds_write_b128 v162, v[136:139] offset:49152
	ds_write_b128 v163, v[140:143] offset:49152
	s_cbranch_vccz .LBB0_932
	s_and_saveexec_b64 s[12:13], s[6:7]
	ds_write_b32 v151, v144 offset:128
	s_or_b64 exec, exec, s[12:13]
	s_waitcnt lgkmcnt(0)
	v_add_u32_e32 v140, s95, v150
	ds_read_b128 v[128:131], v140 offset:224
	ds_read_b128 v[132:135], v140 offset:192
	ds_read_b128 v[136:139], v140 offset:160
	ds_read_b128 v[140:143], v140 offset:128
	s_waitcnt lgkmcnt(3)
	v_pk_mul_f32 v[12:13], v[12:13], v[128:129]
	s_waitcnt lgkmcnt(2)
	v_pk_mul_f32 v[8:9], v[8:9], v[132:133]
	s_waitcnt lgkmcnt(1)
	v_pk_mul_f32 v[4:5], v[4:5], v[136:137]
	v_pk_mul_f32 v[14:15], v[14:15], v[130:131]
	v_pk_mul_f32 v[10:11], v[10:11], v[134:135]
	v_pk_mul_f32 v[6:7], v[6:7], v[138:139]
	s_waitcnt lgkmcnt(0)
	v_pk_mul_f32 v[2:3], v[2:3], v[142:143]
	v_pk_mul_f32 v[0:1], v[0:1], v[140:141]
	v_pk_mul_f32 v[60:61], v[60:61], v[128:129]
	v_pk_mul_f32 v[56:57], v[56:57], v[132:133]
	v_pk_mul_f32 v[52:53], v[52:53], v[136:137]
	v_pk_mul_f32 v[62:63], v[62:63], v[130:131]
	v_pk_mul_f32 v[58:59], v[58:59], v[134:135]
	v_pk_mul_f32 v[54:55], v[54:55], v[138:139]
	v_pk_mul_f32 v[50:51], v[50:51], v[142:143]
	v_pk_mul_f32 v[48:49], v[48:49], v[140:141]
	v_pk_mul_f32 v[44:45], v[44:45], v[128:129]
	v_pk_mul_f32 v[40:41], v[40:41], v[132:133]
	v_pk_mul_f32 v[36:37], v[36:37], v[136:137]
	v_pk_mul_f32 v[46:47], v[46:47], v[130:131]
	v_pk_mul_f32 v[42:43], v[42:43], v[134:135]
	v_pk_mul_f32 v[38:39], v[38:39], v[138:139]
	v_pk_mul_f32 v[34:35], v[34:35], v[142:143]
	v_pk_mul_f32 v[32:33], v[32:33], v[140:141]
	v_pk_mul_f32 v[28:29], v[28:29], v[128:129]
	v_pk_mul_f32 v[24:25], v[24:25], v[132:133]
	v_pk_mul_f32 v[20:21], v[20:21], v[136:137]
	v_pk_mul_f32 v[30:31], v[30:31], v[130:131]
	v_pk_mul_f32 v[26:27], v[26:27], v[134:135]
	v_pk_mul_f32 v[22:23], v[22:23], v[138:139]
	v_pk_mul_f32 v[18:19], v[18:19], v[142:143]
	v_pk_mul_f32 v[16:17], v[16:17], v[140:141]
.LBB0_932:
	v_cndmask_b32_e64 v174, v145, v174, s[8:9]
	v_mul_f32_e32 v128, 0xbe0293ee, v174
	v_pk_fma_f32 v[80:81], v[80:81], s[76:77], v[128:129] op_sel_hi:[1,0,0]
	v_pk_fma_f32 v[82:83], v[82:83], s[76:77], v[128:129] op_sel_hi:[1,0,0]
	v_pk_fma_f32 v[84:85], v[84:85], s[76:77], v[128:129] op_sel_hi:[1,0,0]
	v_pk_fma_f32 v[86:87], v[86:87], s[76:77], v[128:129] op_sel_hi:[1,0,0]
	v_pk_fma_f32 v[88:89], v[88:89], s[76:77], v[128:129] op_sel_hi:[1,0,0]
	v_pk_fma_f32 v[90:91], v[90:91], s[76:77], v[128:129] op_sel_hi:[1,0,0]
	v_pk_fma_f32 v[92:93], v[92:93], s[76:77], v[128:129] op_sel_hi:[1,0,0]
	v_pk_fma_f32 v[94:95], v[94:95], s[76:77], v[128:129] op_sel_hi:[1,0,0]
	v_exp_f32_e32 v145, v80
	v_exp_f32_e32 v187, v81
	v_exp_f32_e32 v146, v82
	v_exp_f32_e32 v188, v83
	v_exp_f32_e32 v186, v84
	v_exp_f32_e32 v189, v85
	v_exp_f32_e32 v147, v86
	v_exp_f32_e32 v185, v87
	v_exp_f32_e32 v157, v88
	v_exp_f32_e32 v181, v89
	v_exp_f32_e32 v179, v90
	v_exp_f32_e32 v182, v91
	v_exp_f32_e32 v154, v92
	v_exp_f32_e32 v155, v93
	v_exp_f32_e32 v156, v94
	v_exp_f32_e32 v180, v95
	v_pk_fma_f32 v[142:143], v[64:65], s[76:77], v[128:129] op_sel_hi:[1,0,0]
	v_add_f32_e32 v64, v175, v176
	s_add_u32 s10, s10, 0x10000
	v_fmac_f32_e32 v64, v173, v158
	v_add_f32_e32 v158, v183, v184
	s_addc_u32 s11, s11, 0
	s_add_i32 s14, s14, 2
	v_pk_fma_f32 v[140:141], v[66:67], s[76:77], v[128:129] op_sel_hi:[1,0,0]
	v_pk_fma_f32 v[136:137], v[68:69], s[76:77], v[128:129] op_sel_hi:[1,0,0]
	v_pk_fma_f32 v[132:133], v[70:71], s[76:77], v[128:129] op_sel_hi:[1,0,0]
	v_pk_fma_f32 v[130:131], v[72:73], s[76:77], v[128:129] op_sel_hi:[1,0,0]
	v_pk_fma_f32 v[138:139], v[74:75], s[76:77], v[128:129] op_sel_hi:[1,0,0]
	v_pk_fma_f32 v[134:135], v[76:77], s[76:77], v[128:129] op_sel_hi:[1,0,0]
	v_pk_fma_f32 v[128:129], v[78:79], s[76:77], v[128:129] op_sel_hi:[1,0,0]
	v_fmac_f32_e32 v158, v64, v177
	s_cmp_ge_u32 s14, s43
	s_waitcnt lgkmcnt(0)
	s_barrier
	s_cbranch_scc1 .LBB0_934
	v_mov_b32_e32 v173, v144
	s_branch .LBB0_924

; __device__ __forceinline__ void finishSM(f32x16& p0, f32x16& p1, float alpha, float& l_reg, bf16x8& pa0, bf16x8& pa1, bf16x8& pa2, bf16x8& pa3) {
; #pragma unroll
;   for (int r = 0; r < 16; ++r) p1[r] = __builtin_amdgcn_exp2f(p1[r]);
;   float ps = 0;
; #pragma unroll
;   for (int r = 0; r < 16; ++r) ps += p0[r];
; #pragma unroll
;   for (int r = 0; r < 16; ++r) ps += p1[r];
;   { auto rr = __builtin_amdgcn_permlane32_swap(__float_as_uint(ps), __float_as_uint(ps), false, false);
;     ps = __uint_as_float(rr[0]) + __uint_as_float(rr[1]); }
;   l_reg = l_reg * alpha + ps;
;     ...
;   PK4(p0, 0, pa0); PK4(p0, 8, pa1); PK4(p1, 0, pa2); PK4(p1, 8, pa3);
;     ...
; }
; template <int DK, int NPARK>
; __device__ __forceinline__ void qkt(f32x16& p0, f32x16& p1, const char* Ks, const bf16x8* qr, const char* qpark, int r32, int hi) {
;   p0 = f32x16{}; p1 = f32x16{};
; #pragma unroll
;   for (int d0 = 0; d0 < DK / 16; ++d0) { const int cb = (d0 * 16 + hi * 8) * 2;
;     bf16x8 b0 = *reinterpret_cast<const bf16x8*>(Ks + kswz<DK>(r32, cb));
;     bf16x8 b1 = *reinterpret_cast<const bf16x8*>(Ks + kswz<DK>(32 + r32, cb));
;     bf16x8 q;
;     if constexpr (NPARK > 0) { if (d0 >= DK / 16 - NPARK) q = *reinterpret_cast<const bf16x8*>(qpark + (d0 - (DK / 16 - NPARK)) * 1024); else q = qr[d0]; } else q = qr[d0];
;     p0 = __builtin_amdgcn_mfma_f32_32x32x16_bf16(b0, q, p0, 0, 0, 0);
;     p1 = __builtin_amdgcn_mfma_f32_32x32x16_bf16(b1, q, p1, 0, 0, 0); }
.LBB0_948:
	ds_read_b128 v[64:67], v196 offset:57344
	ds_read_b128 v[68:71], v216 offset:57344
	ds_read_b128 v[174:177], v199 offset:57344
	ds_read_b128 v[218:221], v214 offset:57344
	v_add_f32_e32 v148, v170, v149
	s_waitcnt lgkmcnt(3)
	v_mfma_f32_32x32x16_bf16 v[80:95], v[64:67], v[124:127], 0
	v_add_f32_e32 v148, v150, v148
	v_add_f32_e32 v148, v171, v148
	v_add_f32_e32 v148, v169, v148
	v_add_f32_e32 v148, v172, v148
	v_add_f32_e32 v148, v151, v148
	v_add_f32_e32 v148, v168, v148
	v_add_f32_e32 v148, v147, v148
	s_waitcnt lgkmcnt(2)
	v_mfma_f32_32x32x16_bf16 v[64:79], v[68:71], v[124:127], 0
	v_add_f32_e32 v148, v152, v148
	v_add_f32_e32 v148, v153, v148
	v_add_f32_e32 v148, v154, v148
	v_exp_f32_e32 v142, v142
	v_add_f32_e32 v148, v144, v148
	v_exp_f32_e32 v143, v143
	v_add_f32_e32 v148, v145, v148
	s_waitcnt lgkmcnt(1)
	v_mfma_f32_32x32x16_bf16 v[80:95], v[174:177], v[116:119], v[80:95]
	v_exp_f32_e32 v140, v140
	v_add_f32_e32 v148, v146, v148
	v_exp_f32_e32 v141, v141
	v_add_f32_e32 v148, v155, v148
	v_exp_f32_e32 v136, v136
	v_add_f32_e32 v148, v142, v148
	v_exp_f32_e32 v137, v137
	s_waitcnt lgkmcnt(0)
	v_mfma_f32_32x32x16_bf16 v[64:79], v[218:221], v[116:119], v[64:79]
	ds_read_b128 v[174:177], v198 offset:57344
	ds_read_b128 v[218:221], v213 offset:57344
	v_add_f32_e32 v148, v143, v148
	v_exp_f32_e32 v132, v132
	v_add_f32_e32 v148, v140, v148
	v_exp_f32_e32 v133, v133
	v_add_f32_e32 v148, v141, v148
	v_exp_f32_e32 v130, v130
	s_waitcnt lgkmcnt(1)
	v_mfma_f32_32x32x16_bf16 v[80:95], v[174:177], v[120:123], v[80:95]
	v_add_f32_e32 v148, v136, v148
	v_exp_f32_e32 v131, v131
	v_add_f32_e32 v148, v137, v148
	v_exp_f32_e32 v138, v138
	v_add_f32_e32 v148, v132, v148
	v_exp_f32_e32 v139, v139
	v_add_f32_e32 v148, v133, v148
	s_waitcnt lgkmcnt(0)
	v_mfma_f32_32x32x16_bf16 v[64:79], v[218:221], v[120:123], v[64:79]
	ds_read_b128 v[174:177], v197 offset:57344
	ds_read_b128 v[218:221], v212 offset:57344
	v_exp_f32_e32 v134, v134
	v_add_f32_e32 v148, v130, v148
	v_exp_f32_e32 v135, v135
	v_add_f32_e32 v148, v131, v148
	v_exp_f32_e32 v128, v128
	v_add_f32_e32 v148, v138, v148
	s_waitcnt lgkmcnt(1)
	v_mfma_f32_32x32x16_bf16 v[80:95], v[174:177], v[112:115], v[80:95]
	v_exp_f32_e32 v129, v129
	v_add_f32_e32 v148, v139, v148
	v_add_f32_e32 v148, v134, v148
	v_add_f32_e32 v148, v135, v148
	v_add_f32_e32 v148, v128, v148
	v_add_f32_e32 v217, v129, v148
	s_waitcnt lgkmcnt(0)
	v_mfma_f32_32x32x16_bf16 v[64:79], v[218:221], v[112:115], v[64:79]
	ds_read_b128 v[174:177], v195 offset:57344
	ds_read_b128 v[218:221], v211 offset:57344
	s_waitcnt lgkmcnt(1)
	v_mfma_f32_32x32x16_bf16 v[80:95], v[174:177], v[108:111], v[80:95]
	s_waitcnt lgkmcnt(0)
	v_mfma_f32_32x32x16_bf16 v[64:79], v[218:221], v[108:111], v[64:79]
	ds_read_b128 v[174:177], v194 offset:57344
	ds_read_b128 v[218:221], v209 offset:57344
	s_waitcnt lgkmcnt(1)
	v_mfma_f32_32x32x16_bf16 v[80:95], v[174:177], v[104:107], v[80:95]
	s_waitcnt lgkmcnt(0)
	v_mfma_f32_32x32x16_bf16 v[64:79], v[218:221], v[104:107], v[64:79]
	ds_read_b128 v[174:177], v188 offset:57344
	ds_read_b128 v[218:221], v208 offset:57344
	s_waitcnt lgkmcnt(1)
	v_mfma_f32_32x32x16_bf16 v[80:95], v[174:177], v[100:103], v[80:95]
	s_waitcnt lgkmcnt(0)
	v_mfma_f32_32x32x16_bf16 v[64:79], v[218:221], v[100:103], v[64:79]
	ds_read_b128 v[174:177], v187 offset:57344
	ds_read_b128 v[218:221], v207 offset:57344
	s_waitcnt lgkmcnt(1)
	v_mfma_f32_32x32x16_bf16 v[80:95], v[174:177], v[96:99], v[80:95]
	s_waitcnt lgkmcnt(0)
	v_mfma_f32_32x32x16_bf16 v[64:79], v[218:221], v[96:99], v[64:79]
	ds_read_b128 v[174:177], v186 offset:57344
	ds_read_b128 v[218:221], v206 offset:57344
	ds_read_b128 v[222:225], v183
	s_waitcnt lgkmcnt(0)
	v_mfma_f32_32x32x16_bf16 v[80:95], v[174:177], v[222:225], v[80:95]
	v_mfma_f32_32x32x16_bf16 v[64:79], v[218:221], v[222:225], v[64:79]
	ds_read_b128 v[174:177], v190 offset:57344
	ds_read_b128 v[218:221], v205 offset:57344
	ds_read_b128 v[222:225], v183 offset:1024
	s_waitcnt lgkmcnt(0)
	v_mfma_f32_32x32x16_bf16 v[80:95], v[174:177], v[222:225], v[80:95]
	v_mfma_f32_32x32x16_bf16 v[64:79], v[218:221], v[222:225], v[64:79]
	ds_read_b128 v[174:177], v201 offset:57344
	ds_read_b128 v[218:221], v204 offset:57344
	ds_read_b128 v[222:225], v183 offset:2048
	s_waitcnt lgkmcnt(0)
	v_mfma_f32_32x32x16_bf16 v[80:95], v[174:177], v[222:225], v[80:95]
	v_mfma_f32_32x32x16_bf16 v[64:79], v[218:221], v[222:225], v[64:79]
	ds_read_b128 v[174:177], v200 offset:57344
	ds_read_b128 v[218:221], v203 offset:57344
	ds_read_b128 v[222:225], v183 offset:3072
	v_cvt_pk_bf16_f32 v148, v149, v170
	v_cvt_pk_bf16_f32 v149, v150, v171
	v_cvt_pk_bf16_f32 v150, v169, v172
	v_cvt_pk_bf16_f32 v151, v151, v168
	v_cvt_pk_bf16_f32 v152, v147, v152
	v_cvt_pk_bf16_f32 v153, v153, v154
	s_waitcnt lgkmcnt(0)
	v_mfma_f32_32x32x16_bf16 v[80:95], v[174:177], v[222:225], v[80:95]
	v_permlane32_swap_b32_e32 v148, v150
	v_cvt_pk_bf16_f32 v154, v144, v145
	v_cvt_pk_bf16_f32 v155, v146, v155
	v_permlane32_swap_b32_e32 v149, v151
	v_permlane32_swap_b32_e32 v152, v154
	v_mfma_f32_32x32x16_bf16 v[64:79], v[218:221], v[222:225], v[64:79]
	v_mov_b32_e32 v218, v217
	s_nop 1
	v_permlane32_swap_b32_e32 v217, v218
	v_cvt_pk_bf16_f32 v220, v142, v143
	v_cvt_pk_bf16_f32 v221, v140, v141
	v_cvt_pk_bf16_f32 v222, v136, v137
	v_cvt_pk_bf16_f32 v223, v132, v133
	v_cvt_pk_bf16_f32 v224, v130, v131
	v_cvt_pk_bf16_f32 v225, v138, v139
	v_cvt_pk_bf16_f32 v226, v134, v135
	v_cvt_pk_bf16_f32 v227, v128, v129
	v_permlane32_swap_b32_e32 v153, v155
	v_permlane32_swap_b32_e32 v220, v222
	v_permlane32_swap_b32_e32 v221, v223
	v_permlane32_swap_b32_e32 v224, v226
	v_permlane32_swap_b32_e32 v225, v227
	s_add_u32 s34, s32, s38
	s_addc_u32 s35, s33, 0
	s_add_u32 s36, s56, s39
	s_addc_u32 s37, s57, 0
	global_load_dwordx4 v[128:131], v251, s[34:35]
	global_load_dwordx4 v[132:135], v252, s[34:35]
	global_load_dwordx4 v[136:139], v248, s[36:37]
	global_load_dwordx4 v[140:143], v249, s[36:37]
	global_load_dwordx4 v[144:147], v250, s[36:37]
	ds_read_b64_tr_b16 v[228:229], v182 offset:0
	ds_read_b64_tr_b16 v[230:231], v182 offset:0x800
	ds_read_b64_tr_b16 v[232:233], v182 offset:0x1000
	ds_read_b64_tr_b16 v[234:235], v182 offset:0x1800
	ds_read_b64_tr_b16 v[236:237], v182 offset:0x2000
	ds_read_b64_tr_b16 v[238:239], v182 offset:0x2800
	ds_read_b64_tr_b16 v[244:245], v182 offset:0x3000
	ds_read_b64_tr_b16 v[246:247], v182 offset:0x3800
	s_waitcnt lgkmcnt(0)
; #define SBAR() __builtin_amdgcn_sched_barrier(0)
; template <int DK>
; __device__ __forceinline__ void partialSM(f32x16& p0, f32x16& p1, float& m_reg, float& mn, float& alpha) {
;   constexpr float SCALE = Cst<DK>::SCALE, C = SCALE * 1.4426950408889634f;
;   float pmax = p0[0];
; #pragma unroll
;   for (int r = 1; r < 16; ++r) pmax = fmaxf(pmax, p0[r]);
; #pragma unroll
;   for (int r = 0; r < 16; ++r) pmax = fmaxf(pmax, p1[r]);
;   { auto rr = __builtin_amdgcn_permlane32_swap(__float_as_uint(pmax), __float_as_uint(pmax), false, false);
;     pmax = fmaxf(__uint_as_float(rr[0]), __uint_as_float(rr[1])); }
;   if (__builtin_expect(__all(pmax - m_reg <= THR / SCALE), 1)) { mn = m_reg; alpha = 1.f; }
;   else { mn = fmaxf(m_reg, pmax); alpha = __builtin_amdgcn_exp2f((m_reg - mn) * C); m_reg = mn; }
; template <int D0> __device__ __forceinline__ void pv_one(f32x16& od, int vb, bf16x8 pa0, bf16x8 pa1, bf16x8 pa2, bf16x8 pa3) {
;   const s16x4 l0 = tr_read<v_rd_off(D0, 0, 0)>(vb), h0 = tr_read<v_rd_off(D0, 0, 1)>(vb), l1 = tr_read<v_rd_off(D0, 1, 0)>(vb), h1 = tr_read<v_rd_off(D0, 1, 1)>(vb);
;   const s16x4 l2 = tr_read<v_rd_off(D0, 2, 0)>(vb), h2 = tr_read<v_rd_off(D0, 2, 1)>(vb), l3 = tr_read<v_rd_off(D0, 3, 0)>(vb), h3 = tr_read<v_rd_off(D0, 3, 1)>(vb);
;   asm volatile("s_waitcnt lgkmcnt(0)" ::: "memory"); SBAR();
;     ...
;   od = __builtin_amdgcn_mfma_f32_32x32x16_bf16(pa0, PK(l0, h0), od, 0, 0, 0);
;   od = __builtin_amdgcn_mfma_f32_32x32x16_bf16(pa1, PK(l1, h1), od, 0, 0, 0);
;   od = __builtin_amdgcn_mfma_f32_32x32x16_bf16(pa2, PK(l2, h2), od, 0, 0, 0);
;   od = __builtin_amdgcn_mfma_f32_32x32x16_bf16(pa3, PK(l3, h3), od, 0, 0, 0);
;     ...
; }
; __device__ __forceinline__ void pv_d0(f32x16* o, int vb, bf16x8 pa0, bf16x8 pa1, bf16x8 pa2, bf16x8 pa3) {
;   pv_one<0>(o[0], vb, pa0, pa1, pa2, pa3); pv_one<1>(o[1], vb, pa0, pa1, pa2, pa3); pv_one<2>(o[2], vb, pa0, pa1, pa2, pa3); pv_one<3>(o[3], vb, pa0, pa1, pa2, pa3);
; }
; template <int DK, int LDQ, int LDK, int LDV, int LDO, int SDEPTH, int NPARK>
; __device__ __forceinline__ void body(const bf16_t* __restrict__ Qb, const bf16_t* __restrict__ Kh, const bf16_t* __restrict__ Vh, bf16_t* __restrict__ Ob, int seq, char* lds, int tid, int wid) {
;   constexpr int SHM_K = KVBLK * DK * 2, ND0 = DK / 16;
;   const int lane = tid & 63, r32 = lane & 31, hi = lane >> 5;
;   char* V_lds = lds; char* K_lds = lds + 2 * SHM_V;
	v_mfma_f32_32x32x16_bf16 v[0:15], v[148:151], v[228:231], v[0:15]
	ds_read_b64_tr_b16 v[228:229], v182 offset:0x200
	ds_read_b64_tr_b16 v[230:231], v182 offset:0xa00
	v_mfma_f32_32x32x16_bf16 v[0:15], v[152:155], v[232:235], v[0:15]
	ds_read_b64_tr_b16 v[232:233], v182 offset:0x1200
	ds_read_b64_tr_b16 v[234:235], v182 offset:0x1a00
	v_mfma_f32_32x32x16_bf16 v[0:15], v[220:223], v[236:239], v[0:15]
	ds_read_b64_tr_b16 v[236:237], v182 offset:0x2200
	ds_read_b64_tr_b16 v[238:239], v182 offset:0x2a00
	v_mfma_f32_32x32x16_bf16 v[0:15], v[224:227], v[244:247], v[0:15]
	ds_read_b64_tr_b16 v[244:245], v182 offset:0x3200
	ds_read_b64_tr_b16 v[246:247], v182 offset:0x3a00
	s_waitcnt lgkmcnt(0)
	v_mfma_f32_32x32x16_bf16 v[48:63], v[148:151], v[228:231], v[48:63]
	ds_read_b64_tr_b16 v[228:229], v182 offset:0x400
	ds_read_b64_tr_b16 v[230:231], v182 offset:0xc00
	v_mfma_f32_32x32x16_bf16 v[48:63], v[152:155], v[232:235], v[48:63]
	ds_read_b64_tr_b16 v[232:233], v182 offset:0x1400
	ds_read_b64_tr_b16 v[234:235], v182 offset:0x1c00
	v_mfma_f32_32x32x16_bf16 v[48:63], v[220:223], v[236:239], v[48:63]
	ds_read_b64_tr_b16 v[236:237], v182 offset:0x2400
	ds_read_b64_tr_b16 v[238:239], v182 offset:0x2c00
	v_mfma_f32_32x32x16_bf16 v[48:63], v[224:227], v[244:247], v[48:63]
	ds_read_b64_tr_b16 v[244:245], v182 offset:0x3400
	ds_read_b64_tr_b16 v[246:247], v182 offset:0x3c00
	s_waitcnt lgkmcnt(0)
	v_mfma_f32_32x32x16_bf16 v[32:47], v[148:151], v[228:231], v[32:47]
	ds_read_b64_tr_b16 v[228:229], v182 offset:0x600
	ds_read_b64_tr_b16 v[230:231], v182 offset:0xe00
	v_mfma_f32_32x32x16_bf16 v[32:47], v[152:155], v[232:235], v[32:47]
	ds_read_b64_tr_b16 v[232:233], v182 offset:0x1600
	ds_read_b64_tr_b16 v[234:235], v182 offset:0x1e00
	v_mfma_f32_32x32x16_bf16 v[32:47], v[220:223], v[236:239], v[32:47]
	ds_read_b64_tr_b16 v[236:237], v182 offset:0x2600
	ds_read_b64_tr_b16 v[238:239], v182 offset:0x2e00
	v_mfma_f32_32x32x16_bf16 v[32:47], v[224:227], v[244:247], v[32:47]
	ds_read_b64_tr_b16 v[244:245], v182 offset:0x3600
	ds_read_b64_tr_b16 v[246:247], v182 offset:0x3e00
	s_waitcnt lgkmcnt(0)
	v_mfma_f32_32x32x16_bf16 v[16:31], v[148:151], v[228:231], v[16:31]
	v_max_f32_e32 v148, v80, v81
	v_max3_f32 v148, v148, v82, v83
	v_max3_f32 v148, v148, v84, v85
	v_max3_f32 v148, v148, v86, v87
	v_max3_f32 v148, v148, v88, v89
	v_max3_f32 v148, v148, v90, v91
	v_max3_f32 v148, v148, v92, v93
	v_mfma_f32_32x32x16_bf16 v[16:31], v[152:155], v[232:235], v[16:31]
	v_max3_f32 v148, v148, v94, v95
	v_max3_f32 v148, v148, v64, v65
	v_max3_f32 v148, v148, v66, v67
	v_max3_f32 v148, v148, v68, v69
	v_max3_f32 v148, v148, v70, v71
	v_max3_f32 v148, v148, v72, v73
	v_max3_f32 v148, v148, v74, v75
	v_max3_f32 v148, v148, v76, v77
	v_mfma_f32_32x32x16_bf16 v[16:31], v[220:223], v[236:239], v[16:31]
	v_max3_f32 v148, v148, v78, v79
	v_mov_b32_e32 v149, v148
	s_nop 1
	v_permlane32_swap_b32_e32 v148, v149
	v_max_f32_e32 v148, v148, v149
	v_sub_f32_e32 v149, v148, v210
	v_cmp_ge_f32_e32 vcc, s69, v149
	v_max_f32_e32 v148, v210, v148
	v_mfma_f32_32x32x16_bf16 v[16:31], v[224:227], v[244:247], v[16:31]
	v_sub_f32_e32 v149, v210, v148
	v_mul_f32_e32 v149, 0x3dd53b94, v149
	v_exp_f32_e32 v149, v149
	s_cmp_eq_u64 vcc, exec
	s_cselect_b64 s[8:9], -1, 0
	s_barrier
	s_waitcnt vmcnt(0)
	v_cndmask_b32_e64 v219, v149, 1.0, s[8:9]
	v_cmp_gt_f32_e32 vcc, 1.0, v219
	ds_write_b128 v184, v[128:131]
	ds_write_b128 v185, v[132:135]
	ds_write_b128 v189, v[136:139] offset:32768
	ds_write_b128 v189, v[140:143] offset:45056
	ds_write_b128 v191, v[144:147] offset:32768
	s_cbranch_vccz .LBB0_952
	s_and_saveexec_b64 s[12:13], s[6:7]
	ds_write_b32 v179, v219 offset:128
	s_or_b64 exec, exec, s[12:13]
	s_waitcnt lgkmcnt(0)
	v_add_u32_e32 v140, s59, v192
	ds_read_b128 v[128:131], v140 offset:224
	ds_read_b128 v[132:135], v140 offset:192
	ds_read_b128 v[136:139], v140 offset:160
	ds_read_b128 v[140:143], v140 offset:128
	s_waitcnt lgkmcnt(3)
	v_pk_mul_f32 v[12:13], v[12:13], v[128:129]
	s_waitcnt lgkmcnt(2)
	v_pk_mul_f32 v[8:9], v[8:9], v[132:133]
	s_waitcnt lgkmcnt(1)
	v_pk_mul_f32 v[4:5], v[4:5], v[136:137]
	v_pk_mul_f32 v[14:15], v[14:15], v[130:131]
	v_pk_mul_f32 v[10:11], v[10:11], v[134:135]
	v_pk_mul_f32 v[6:7], v[6:7], v[138:139]
	s_waitcnt lgkmcnt(0)
	v_pk_mul_f32 v[2:3], v[2:3], v[142:143]
	v_pk_mul_f32 v[0:1], v[0:1], v[140:141]
	v_pk_mul_f32 v[60:61], v[60:61], v[128:129]
	v_pk_mul_f32 v[56:57], v[56:57], v[132:133]
	v_pk_mul_f32 v[52:53], v[52:53], v[136:137]
	v_pk_mul_f32 v[62:63], v[62:63], v[130:131]
	v_pk_mul_f32 v[58:59], v[58:59], v[134:135]
	v_pk_mul_f32 v[54:55], v[54:55], v[138:139]
	v_pk_mul_f32 v[50:51], v[50:51], v[142:143]
	v_pk_mul_f32 v[48:49], v[48:49], v[140:141]
	v_pk_mul_f32 v[44:45], v[44:45], v[128:129]
	v_pk_mul_f32 v[40:41], v[40:41], v[132:133]
	v_pk_mul_f32 v[36:37], v[36:37], v[136:137]
	v_pk_mul_f32 v[46:47], v[46:47], v[130:131]
	v_pk_mul_f32 v[42:43], v[42:43], v[134:135]
	v_pk_mul_f32 v[38:39], v[38:39], v[138:139]
	v_pk_mul_f32 v[34:35], v[34:35], v[142:143]
	v_pk_mul_f32 v[32:33], v[32:33], v[140:141]
	v_pk_mul_f32 v[28:29], v[28:29], v[128:129]
	v_pk_mul_f32 v[24:25], v[24:25], v[132:133]
	v_pk_mul_f32 v[20:21], v[20:21], v[136:137]
	v_pk_mul_f32 v[30:31], v[30:31], v[130:131]
	v_pk_mul_f32 v[26:27], v[26:27], v[134:135]
	v_pk_mul_f32 v[22:23], v[22:23], v[138:139]
	v_pk_mul_f32 v[18:19], v[18:19], v[142:143]
	v_pk_mul_f32 v[16:17], v[16:17], v[140:141]
; template <int DK>
; __device__ __forceinline__ void partialSM(f32x16& p0, f32x16& p1, float& m_reg, float& mn, float& alpha) {
;     ...
;   float mnC = -mn * C;
; #pragma unroll
;   for (int r = 0; r < 16; ++r) p0[r] = fmaf(p0[r], C, mnC);
; #pragma unroll
;   for (int r = 0; r < 16; ++r) p1[r] = fmaf(p1[r], C, mnC);
; #pragma unroll
;   for (int r = 0; r < 16; ++r) p0[r] = __builtin_amdgcn_exp2f(p0[r]);
; }
; __device__ __forceinline__ void finishSM(f32x16& p0, f32x16& p1, float alpha, float& l_reg, bf16x8& pa0, bf16x8& pa1, bf16x8& pa2, bf16x8& pa3) {
; #pragma unroll
;   for (int r = 0; r < 16; ++r) p1[r] = __builtin_amdgcn_exp2f(p1[r]);
;   float ps = 0;
; #pragma unroll
;   for (int r = 0; r < 16; ++r) ps += p0[r];
; #pragma unroll
;   for (int r = 0; r < 16; ++r) ps += p1[r];
;   { auto rr = __builtin_amdgcn_permlane32_swap(__float_as_uint(ps), __float_as_uint(ps), false, false);
;     ps = __uint_as_float(rr[0]) + __uint_as_float(rr[1]); }
;   l_reg = l_reg * alpha + ps;
;     ...
;   PK4(p0, 0, pa0); PK4(p0, 8, pa1); PK4(p1, 0, pa2); PK4(p1, 8, pa3);
;     ...
; }
; template <int DK, int NPARK>
; __device__ __forceinline__ void qkt(f32x16& p0, f32x16& p1, const char* Ks, const bf16x8* qr, const char* qpark, int r32, int hi) {
;   p0 = f32x16{}; p1 = f32x16{};
; #pragma unroll
;   for (int d0 = 0; d0 < DK / 16; ++d0) { const int cb = (d0 * 16 + hi * 8) * 2;
;     bf16x8 b0 = *reinterpret_cast<const bf16x8*>(Ks + kswz<DK>(r32, cb));
;     bf16x8 b1 = *reinterpret_cast<const bf16x8*>(Ks + kswz<DK>(32 + r32, cb));
;     bf16x8 q;
;     if constexpr (NPARK > 0) { if (d0 >= DK / 16 - NPARK) q = *reinterpret_cast<const bf16x8*>(qpark + (d0 - (DK / 16 - NPARK)) * 1024); else q = qr[d0]; } else q = qr[d0];
;     p0 = __builtin_amdgcn_mfma_f32_32x32x16_bf16(b0, q, p0, 0, 0, 0);
;     p1 = __builtin_amdgcn_mfma_f32_32x32x16_bf16(b1, q, p1, 0, 0, 0); }
.LBB0_952:
	v_cndmask_b32_e64 v210, v148, v210, s[8:9]
	v_mul_f32_e32 v144, 0xbdd53b94, v210
	v_pk_fma_f32 v[80:81], v[80:81], s[78:79], v[144:145] op_sel_hi:[1,0,0]
	v_pk_fma_f32 v[82:83], v[82:83], s[78:79], v[144:145] op_sel_hi:[1,0,0]
	v_pk_fma_f32 v[84:85], v[84:85], s[78:79], v[144:145] op_sel_hi:[1,0,0]
	v_pk_fma_f32 v[86:87], v[86:87], s[78:79], v[144:145] op_sel_hi:[1,0,0]
	v_pk_fma_f32 v[88:89], v[88:89], s[78:79], v[144:145] op_sel_hi:[1,0,0]
	v_pk_fma_f32 v[90:91], v[90:91], s[78:79], v[144:145] op_sel_hi:[1,0,0]
	v_pk_fma_f32 v[92:93], v[92:93], s[78:79], v[144:145] op_sel_hi:[1,0,0]
	v_pk_fma_f32 v[94:95], v[94:95], s[78:79], v[144:145] op_sel_hi:[1,0,0]
	v_fmamk_f32 v220, v67, 0x3dd53b94, v144
	v_fmamk_f32 v221, v68, 0x3dd53b94, v144
	v_fmamk_f32 v148, v71, 0x3dd53b94, v144
	v_fmamk_f32 v149, v72, 0x3dd53b94, v144
	v_fmamk_f32 v153, v64, 0x3dd53b94, v144
	v_fmamk_f32 v154, v65, 0x3dd53b94, v144
	v_fmamk_f32 v155, v66, 0x3dd53b94, v144
	v_fmamk_f32 v146, v69, 0x3dd53b94, v144
	v_fmamk_f32 v147, v70, 0x3dd53b94, v144
	v_fmamk_f32 v150, v73, 0x3dd53b94, v144
	v_fmamk_f32 v151, v74, 0x3dd53b94, v144
	v_fmamk_f32 v152, v75, 0x3dd53b94, v144
	v_fmamk_f32 v145, v76, 0x3dd53b94, v144
	v_exp_f32_e32 v141, v80
	v_exp_f32_e32 v143, v81
	v_exp_f32_e32 v139, v82
	v_exp_f32_e32 v142, v83
	v_exp_f32_e32 v138, v84
	v_exp_f32_e32 v140, v85
	v_exp_f32_e32 v136, v86
	v_exp_f32_e32 v137, v87
	v_exp_f32_e32 v133, v88
	v_exp_f32_e32 v135, v89
	v_exp_f32_e32 v132, v90
	v_exp_f32_e32 v134, v91
	v_exp_f32_e32 v129, v92
	v_exp_f32_e32 v131, v93
	v_exp_f32_e32 v128, v94
	v_exp_f32_e32 v130, v95
	v_fmamk_f32 v222, v77, 0x3dd53b94, v144
	v_fmamk_f32 v223, v78, 0x3dd53b94, v144
	v_fmac_f32_e32 v144, 0x3dd53b94, v79
	s_waitcnt lgkmcnt(0)
	s_barrier
	ds_read_b128 v[64:67], v196 offset:32768
	ds_read_b128 v[68:71], v196 offset:45056
	ds_read_b128 v[224:227], v199 offset:32768
	ds_read_b128 v[228:231], v199 offset:45056
	v_exp_f32_e32 v146, v146
	v_exp_f32_e32 v147, v147
	s_waitcnt lgkmcnt(3)
	v_mfma_f32_32x32x16_bf16 v[80:95], v[64:67], v[124:127], 0
	v_exp_f32_e32 v145, v145
	v_exp_f32_e32 v144, v144
	s_waitcnt lgkmcnt(2)
	v_mfma_f32_32x32x16_bf16 v[64:79], v[68:71], v[124:127], 0
	s_waitcnt lgkmcnt(0)
	v_mfma_f32_32x32x16_bf16 v[64:79], v[228:231], v[116:119], v[64:79]
	v_mfma_f32_32x32x16_bf16 v[80:95], v[224:227], v[116:119], v[80:95]
	ds_read_b128 v[224:227], v198 offset:32768
	ds_read_b128 v[228:231], v198 offset:45056
	s_waitcnt lgkmcnt(0)
	v_mfma_f32_32x32x16_bf16 v[64:79], v[228:231], v[120:123], v[64:79]
	v_mfma_f32_32x32x16_bf16 v[80:95], v[224:227], v[120:123], v[80:95]
	ds_read_b128 v[224:227], v197 offset:32768
	ds_read_b128 v[228:231], v197 offset:45056
	s_waitcnt lgkmcnt(0)
	v_mfma_f32_32x32x16_bf16 v[64:79], v[228:231], v[112:115], v[64:79]
	v_mfma_f32_32x32x16_bf16 v[80:95], v[224:227], v[112:115], v[80:95]
	ds_read_b128 v[224:227], v195 offset:32768
	ds_read_b128 v[228:231], v195 offset:45056
	s_waitcnt lgkmcnt(0)
	v_mfma_f32_32x32x16_bf16 v[64:79], v[228:231], v[108:111], v[64:79]
	v_mfma_f32_32x32x16_bf16 v[80:95], v[224:227], v[108:111], v[80:95]
	ds_read_b128 v[224:227], v194 offset:32768
	ds_read_b128 v[228:231], v194 offset:45056
	s_waitcnt lgkmcnt(0)
	v_mfma_f32_32x32x16_bf16 v[64:79], v[228:231], v[104:107], v[64:79]
	v_mfma_f32_32x32x16_bf16 v[80:95], v[224:227], v[104:107], v[80:95]
	ds_read_b128 v[224:227], v188 offset:32768
	ds_read_b128 v[228:231], v188 offset:45056
	s_waitcnt lgkmcnt(0)
	v_mfma_f32_32x32x16_bf16 v[64:79], v[228:231], v[100:103], v[64:79]
	v_mfma_f32_32x32x16_bf16 v[80:95], v[224:227], v[100:103], v[80:95]
	ds_read_b128 v[224:227], v187 offset:32768
	ds_read_b128 v[228:231], v187 offset:45056
	s_waitcnt lgkmcnt(0)
	v_mfma_f32_32x32x16_bf16 v[64:79], v[228:231], v[96:99], v[64:79]
	v_mfma_f32_32x32x16_bf16 v[80:95], v[224:227], v[96:99], v[80:95]
	ds_read_b128 v[224:227], v186 offset:32768
	ds_read_b128 v[228:231], v186 offset:45056
	ds_read_b128 v[232:235], v183
	s_waitcnt lgkmcnt(0)
	v_mfma_f32_32x32x16_bf16 v[64:79], v[228:231], v[232:235], v[64:79]
	v_mfma_f32_32x32x16_bf16 v[80:95], v[224:227], v[232:235], v[80:95]
	ds_read_b128 v[224:227], v190 offset:32768
	ds_read_b128 v[228:231], v190 offset:45056
	ds_read_b128 v[232:235], v183 offset:1024
	s_waitcnt lgkmcnt(0)
	v_mfma_f32_32x32x16_bf16 v[64:79], v[228:231], v[232:235], v[64:79]
	v_mfma_f32_32x32x16_bf16 v[80:95], v[224:227], v[232:235], v[80:95]
	ds_read_b128 v[224:227], v201 offset:32768
	ds_read_b128 v[228:231], v201 offset:45056
	ds_read_b128 v[232:235], v183 offset:2048
	s_waitcnt lgkmcnt(0)
	v_mfma_f32_32x32x16_bf16 v[64:79], v[228:231], v[232:235], v[64:79]
	v_mfma_f32_32x32x16_bf16 v[80:95], v[224:227], v[232:235], v[80:95]
	ds_read_b128 v[224:227], v200 offset:32768
	ds_read_b128 v[228:231], v200 offset:45056
	ds_read_b128 v[232:235], v183 offset:3072
	s_waitcnt lgkmcnt(0)
; __device__ __forceinline__ void finishSM(f32x16& p0, f32x16& p1, float alpha, float& l_reg, bf16x8& pa0, bf16x8& pa1, bf16x8& pa2, bf16x8& pa3) {
; #pragma unroll
;   for (int r = 0; r < 16; ++r) p1[r] = __builtin_amdgcn_exp2f(p1[r]);
;   float ps = 0;
; #pragma unroll
;   for (int r = 0; r < 16; ++r) ps += p0[r];
; #pragma unroll
;   for (int r = 0; r < 16; ++r) ps += p1[r];
;   { auto rr = __builtin_amdgcn_permlane32_swap(__float_as_uint(ps), __float_as_uint(ps), false, false);
;     ps = __uint_as_float(rr[0]) + __uint_as_float(rr[1]); }
;   l_reg = l_reg * alpha + ps;
;     ...
;   PK4(p0, 0, pa0); PK4(p0, 8, pa1); PK4(p1, 0, pa2); PK4(p1, 8, pa3);
;     ...
; }
; template <int DK, int NPARK>
; __device__ __forceinline__ void qkt(f32x16& p0, f32x16& p1, const char* Ks, const bf16x8* qr, const char* qpark, int r32, int hi) {
;   p0 = f32x16{}; p1 = f32x16{};
; #pragma unroll
;   for (int d0 = 0; d0 < DK / 16; ++d0) { const int cb = (d0 * 16 + hi * 8) * 2;
;     bf16x8 b0 = *reinterpret_cast<const bf16x8*>(Ks + kswz<DK>(r32, cb));
;     bf16x8 b1 = *reinterpret_cast<const bf16x8*>(Ks + kswz<DK>(32 + r32, cb));
;     bf16x8 q;
;     if constexpr (NPARK > 0) { if (d0 >= DK / 16 - NPARK) q = *reinterpret_cast<const bf16x8*>(qpark + (d0 - (DK / 16 - NPARK)) * 1024); else q = qr[d0]; } else q = qr[d0];
;     p0 = __builtin_amdgcn_mfma_f32_32x32x16_bf16(b0, q, p0, 0, 0, 0);
;     p1 = __builtin_amdgcn_mfma_f32_32x32x16_bf16(b1, q, p1, 0, 0, 0); }
; }
; __device__ __forceinline__ int v_st(int k, int c) { const int kk = (k & ~0xC) | ((k & 4) << 1) | ((k & 8) >> 1); return ((kk >> 3) * 4 + (c >> 5)) * 512 + ((kk & 7) * 32 + (c & 31)) * 2; }
; __device__ __forceinline__ int v_rd_base(int lane) { return ((lane & 3) << 3) | (((lane >> 2) & 3) << 6) | (((lane >> 4) & 1) << 5) | (((lane >> 5) & 1) << 8); }
; template <int OFF> __device__ __forceinline__ s16x4 tr_read(int vb) {
;   s16x4 r; asm volatile("ds_read_b64_tr_b16 %0, %1 offset:%2" : "=&v"(r) : "v"(vb), "i"(OFF) : "memory"); return r;
; }
; template <int D0> __device__ __forceinline__ void pv_one(f32x16& od, int vb, bf16x8 pa0, bf16x8 pa1, bf16x8 pa2, bf16x8 pa3) {
;   const s16x4 l0 = tr_read<v_rd_off(D0, 0, 0)>(vb), h0 = tr_read<v_rd_off(D0, 0, 1)>(vb), l1 = tr_read<v_rd_off(D0, 1, 0)>(vb), h1 = tr_read<v_rd_off(D0, 1, 1)>(vb);
	v_mfma_f32_32x32x16_bf16 v[64:79], v[228:231], v[232:235], v[64:79]
	v_exp_f32_e32 v229, v148
	v_add_f32_e32 v148, v143, v141
	v_add_f32_e32 v148, v139, v148
	v_add_f32_e32 v148, v142, v148
	v_add_f32_e32 v148, v138, v148
	v_add_f32_e32 v148, v140, v148
	v_add_f32_e32 v148, v136, v148
	v_add_f32_e32 v148, v137, v148
	v_add_f32_e32 v148, v133, v148
	v_add_f32_e32 v148, v135, v148
	v_add_f32_e32 v148, v132, v148
	v_add_f32_e32 v148, v134, v148
	v_mfma_f32_32x32x16_bf16 v[80:95], v[224:227], v[232:235], v[80:95]
	v_exp_f32_e32 v224, v153
	v_add_f32_e32 v148, v129, v148
	v_exp_f32_e32 v225, v154
	v_add_f32_e32 v148, v131, v148
	v_exp_f32_e32 v226, v155
	v_add_f32_e32 v148, v128, v148
	v_exp_f32_e32 v227, v220
	v_add_f32_e32 v148, v130, v148
	v_exp_f32_e32 v228, v221
	v_add_f32_e32 v148, v224, v148
	v_add_f32_e32 v148, v225, v148
	v_add_f32_e32 v148, v226, v148
	v_add_f32_e32 v148, v227, v148
	v_exp_f32_e32 v230, v149
	v_add_f32_e32 v148, v228, v148
	v_exp_f32_e32 v231, v150
	v_add_f32_e32 v148, v146, v148
	v_exp_f32_e32 v232, v151
	v_add_f32_e32 v148, v147, v148
	v_exp_f32_e32 v233, v152
	v_add_f32_e32 v148, v229, v148
	v_add_f32_e32 v148, v230, v148
	v_exp_f32_e32 v234, v222
	v_add_f32_e32 v148, v231, v148
	v_exp_f32_e32 v235, v223
	v_add_f32_e32 v148, v232, v148
	v_add_f32_e32 v148, v233, v148
	v_add_f32_e32 v148, v145, v148
	v_add_f32_e32 v148, v234, v148
	v_add_f32_e32 v148, v235, v148
	v_add_f32_e32 v220, v144, v148
	v_mov_b32_e32 v221, v220
	v_cvt_pk_bf16_f32 v148, v141, v143
	v_cvt_pk_bf16_f32 v149, v139, v142
	v_cvt_pk_bf16_f32 v150, v138, v140
	v_cvt_pk_bf16_f32 v151, v136, v137
	s_nop 1
	v_permlane32_swap_b32_e32 v220, v221
	v_permlane32_swap_b32_e32 v148, v150
	v_permlane32_swap_b32_e32 v149, v151
	v_cvt_pk_bf16_f32 v152, v133, v135
	v_cvt_pk_bf16_f32 v153, v132, v134
	v_cvt_pk_bf16_f32 v154, v129, v131
	v_cvt_pk_bf16_f32 v155, v128, v130
	v_cvt_pk_bf16_f32 v222, v224, v225
	v_cvt_pk_bf16_f32 v223, v226, v227
	v_cvt_pk_bf16_f32 v224, v228, v146
	v_cvt_pk_bf16_f32 v225, v147, v229
	v_cvt_pk_bf16_f32 v226, v230, v231
	v_cvt_pk_bf16_f32 v227, v232, v233
	v_cvt_pk_bf16_f32 v228, v145, v234
	v_cvt_pk_bf16_f32 v229, v235, v144
	s_nop 0
	v_permlane32_swap_b32_e32 v152, v154
	v_permlane32_swap_b32_e32 v153, v155
	v_permlane32_swap_b32_e32 v222, v224
	v_permlane32_swap_b32_e32 v223, v225
	v_permlane32_swap_b32_e32 v226, v228
	v_permlane32_swap_b32_e32 v227, v229
	s_add_u32 s34, s32, s63
	s_addc_u32 s35, s33, 0
	s_add_u32 s36, s56, s82
	s_addc_u32 s37, s57, 0
	global_load_dwordx4 v[128:131], v251, s[34:35]
	global_load_dwordx4 v[132:135], v252, s[34:35]
	global_load_dwordx4 v[136:139], v248, s[36:37]
	global_load_dwordx4 v[140:143], v249, s[36:37]
	global_load_dwordx4 v[144:147], v250, s[36:37]
	ds_read_b64_tr_b16 v[168:169], v181 offset:0
	ds_read_b64_tr_b16 v[170:171], v181 offset:0x800
	ds_read_b64_tr_b16 v[172:173], v181 offset:0x1000
	ds_read_b64_tr_b16 v[174:175], v181 offset:0x1800
	ds_read_b64_tr_b16 v[230:231], v181 offset:0x2000
	ds_read_b64_tr_b16 v[232:233], v181 offset:0x2800
	ds_read_b64_tr_b16 v[234:235], v181 offset:0x3000
	ds_read_b64_tr_b16 v[236:237], v181 offset:0x3800
	s_waitcnt lgkmcnt(0)
	v_mfma_f32_32x32x16_bf16 v[0:15], v[148:151], v[168:171], v[0:15]
	ds_read_b64_tr_b16 v[168:169], v181 offset:0x200
	ds_read_b64_tr_b16 v[170:171], v181 offset:0xa00
	v_mfma_f32_32x32x16_bf16 v[0:15], v[152:155], v[172:175], v[0:15]
	ds_read_b64_tr_b16 v[172:173], v181 offset:0x1200
	ds_read_b64_tr_b16 v[174:175], v181 offset:0x1a00
	v_mfma_f32_32x32x16_bf16 v[0:15], v[222:225], v[230:233], v[0:15]
	ds_read_b64_tr_b16 v[230:231], v181 offset:0x2200
	ds_read_b64_tr_b16 v[232:233], v181 offset:0x2a00
	v_mfma_f32_32x32x16_bf16 v[0:15], v[226:229], v[234:237], v[0:15]
	ds_read_b64_tr_b16 v[234:235], v181 offset:0x3200
	ds_read_b64_tr_b16 v[236:237], v181 offset:0x3a00
	s_waitcnt lgkmcnt(0)
	v_mfma_f32_32x32x16_bf16 v[48:63], v[148:151], v[168:171], v[48:63]
	ds_read_b64_tr_b16 v[168:169], v181 offset:0x400
	ds_read_b64_tr_b16 v[170:171], v181 offset:0xc00
	v_mfma_f32_32x32x16_bf16 v[48:63], v[152:155], v[172:175], v[48:63]
	ds_read_b64_tr_b16 v[172:173], v181 offset:0x1400
	ds_read_b64_tr_b16 v[174:175], v181 offset:0x1c00
	v_mfma_f32_32x32x16_bf16 v[48:63], v[222:225], v[230:233], v[48:63]
	ds_read_b64_tr_b16 v[230:231], v181 offset:0x2400
	ds_read_b64_tr_b16 v[232:233], v181 offset:0x2c00
	v_mfma_f32_32x32x16_bf16 v[48:63], v[226:229], v[234:237], v[48:63]
	ds_read_b64_tr_b16 v[234:235], v181 offset:0x3400
	ds_read_b64_tr_b16 v[236:237], v181 offset:0x3c00
	s_waitcnt lgkmcnt(0)
	v_mfma_f32_32x32x16_bf16 v[32:47], v[148:151], v[168:171], v[32:47]
	ds_read_b64_tr_b16 v[168:169], v181 offset:0x600
	ds_read_b64_tr_b16 v[170:171], v181 offset:0xe00
	v_mfma_f32_32x32x16_bf16 v[32:47], v[152:155], v[172:175], v[32:47]
	ds_read_b64_tr_b16 v[172:173], v181 offset:0x1600
	ds_read_b64_tr_b16 v[174:175], v181 offset:0x1e00
	v_mfma_f32_32x32x16_bf16 v[32:47], v[222:225], v[230:233], v[32:47]
	ds_read_b64_tr_b16 v[230:231], v181 offset:0x2600
	ds_read_b64_tr_b16 v[232:233], v181 offset:0x2e00
	v_mfma_f32_32x32x16_bf16 v[32:47], v[226:229], v[234:237], v[32:47]
	ds_read_b64_tr_b16 v[234:235], v181 offset:0x3600
	ds_read_b64_tr_b16 v[236:237], v181 offset:0x3e00
	s_waitcnt lgkmcnt(0)
	v_mfma_f32_32x32x16_bf16 v[16:31], v[148:151], v[168:171], v[16:31]
	v_max_f32_e32 v148, v80, v81
	v_max3_f32 v148, v148, v82, v83
	v_max3_f32 v148, v148, v84, v85
	v_max3_f32 v148, v148, v86, v87
	v_max3_f32 v148, v148, v88, v89
	v_max3_f32 v148, v148, v90, v91
	v_max3_f32 v148, v148, v92, v93
	v_mfma_f32_32x32x16_bf16 v[16:31], v[152:155], v[172:175], v[16:31]
	v_max3_f32 v148, v148, v94, v95
	v_max3_f32 v148, v148, v64, v65
	v_max3_f32 v148, v148, v66, v67
	v_max3_f32 v148, v148, v68, v69
	v_max3_f32 v148, v148, v70, v71
	v_max3_f32 v148, v148, v72, v73
	v_max3_f32 v148, v148, v74, v75
	v_max3_f32 v148, v148, v76, v77
	v_mfma_f32_32x32x16_bf16 v[16:31], v[222:225], v[230:233], v[16:31]
	v_max3_f32 v148, v148, v78, v79
	v_mov_b32_e32 v149, v148
	s_nop 1
	v_permlane32_swap_b32_e32 v148, v149
	v_max_f32_e32 v148, v148, v149
	v_sub_f32_e32 v149, v148, v210
	v_cmp_ge_f32_e32 vcc, s69, v149
	v_max_f32_e32 v149, v210, v148
	v_mfma_f32_32x32x16_bf16 v[16:31], v[226:229], v[234:237], v[16:31]
	v_sub_f32_e32 v148, v210, v149
	v_mul_f32_e32 v148, 0x3dd53b94, v148
	v_exp_f32_e32 v148, v148
	s_cmp_eq_u64 vcc, exec
	s_cselect_b64 s[8:9], -1, 0
	s_barrier
; #define SBAR() __builtin_amdgcn_sched_barrier(0)
; template <int DK>
; __device__ __forceinline__ void partialSM(f32x16& p0, f32x16& p1, float& m_reg, float& mn, float& alpha) {
;     ...
;   if (__builtin_expect(__all(pmax - m_reg <= THR / SCALE), 1)) { mn = m_reg; alpha = 1.f; }
;   else { mn = fmaxf(m_reg, pmax); alpha = __builtin_amdgcn_exp2f((m_reg - mn) * C); m_reg = mn; }
;   float mnC = -mn * C;
; #pragma unroll
;   for (int r = 0; r < 16; ++r) p0[r] = fmaf(p0[r], C, mnC);
; #pragma unroll
;   for (int r = 0; r < 16; ++r) p1[r] = fmaf(p1[r], C, mnC);
; #pragma unroll
;   for (int r = 0; r < 16; ++r) p0[r] = __builtin_amdgcn_exp2f(p0[r]);
; template <int DK, int LDQ, int LDK, int LDV, int LDO, int SDEPTH, int NPARK>
; __device__ __forceinline__ void body(const bf16_t* __restrict__ Qb, const bf16_t* __restrict__ Kh, const bf16_t* __restrict__ Vh, bf16_t* __restrict__ Ob, int seq, char* lds, int tid, int wid) {
;     ...
;   f32x16 pA0, pA1, pB0, pB1; float mnA, mnB, alA, alB; bf16x8 pa0, pa1, pa2, pa3; const int NT = seq / KVBLK;
;   constexpr int SE = 0, SO = SDEPTH - 1;
;   SLOAD(SE, 0); asm volatile("s_waitcnt vmcnt(0)" ::: "memory"); SWRITE(0, SE); __syncthreads();
;   qkt<DK, NPARK>(pA0, pA1, K_lds, qr, qpark, r32, hi); partialSM<DK>(pA0, pA1, m_reg, mnA, alA);
;   SLOAD(SO, KVBLK); if constexpr (SDEPTH == 2) { if (2 < NT) SLOAD(SE, 2 * KVBLK); }
;   SWAIT(); SWRITE(1, SO); __syncthreads();
;   for (int j = 1; j + 1 < NT; j += 2) {
;     SBAR(); qkt<DK, NPARK>(pB0, pB1, K_lds + SHM_K, qr, qpark, r32, hi);
;     finishSM(pA0, pA1, alA, l_reg, pa0, pa1, pa2, pa3); SBAR();
;     SLOAD(SO, (j + SDEPTH) * KVBLK); SBAR();
;     pv_d0(o, vb0, pa0, pa1, pa2, pa3); partialSM<DK>(pB0, pB1, m_reg, mnB, alB);
;     __syncthreads(); SWAIT(); SWRITE(0, SE);
;     RESC(alB); __syncthreads();
;     SBAR(); qkt<DK, NPARK>(pA0, pA1, K_lds, qr, qpark, r32, hi);
;     finishSM(pB0, pB1, alB, l_reg, pa0, pa1, pa2, pa3); SBAR();
;     if (SDEPTH == 1 || j + 3 < NT) SLOAD(SE, (j + 1 + SDEPTH) * KVBLK); SBAR();
;     pv_d0(o, vb0 + (int)SHM_V, pa0, pa1, pa2, pa3); partialSM<DK>(pA0, pA1, m_reg, mnA, alA);
;     __syncthreads(); SWAIT(); SWRITE(1, SO);
;     RESC(alA); __syncthreads();
	s_waitcnt vmcnt(0)
	v_cndmask_b32_e64 v148, v148, 1.0, s[8:9]
	v_cmp_gt_f32_e32 vcc, 1.0, v148
	ds_write_b128 v184, v[128:131] offset:16384
	ds_write_b128 v185, v[132:135] offset:16384
	ds_write_b128 v189, v[136:139] offset:57344
	ds_write_b128 v202, v[140:143] offset:57344
	ds_write_b128 v191, v[144:147] offset:57344
	s_cbranch_vccz .LBB0_956
	s_and_saveexec_b64 s[12:13], s[6:7]
	ds_write_b32 v179, v148 offset:128
	s_or_b64 exec, exec, s[12:13]
	s_waitcnt lgkmcnt(0)
	v_add_u32_e32 v140, s59, v192
	ds_read_b128 v[128:131], v140 offset:224
	ds_read_b128 v[132:135], v140 offset:192
	ds_read_b128 v[136:139], v140 offset:160
	ds_read_b128 v[140:143], v140 offset:128
	s_waitcnt lgkmcnt(3)
	v_pk_mul_f32 v[12:13], v[12:13], v[128:129]
	s_waitcnt lgkmcnt(2)
	v_pk_mul_f32 v[8:9], v[8:9], v[132:133]
	s_waitcnt lgkmcnt(1)
	v_pk_mul_f32 v[4:5], v[4:5], v[136:137]
	v_pk_mul_f32 v[14:15], v[14:15], v[130:131]
	v_pk_mul_f32 v[10:11], v[10:11], v[134:135]
	v_pk_mul_f32 v[6:7], v[6:7], v[138:139]
	s_waitcnt lgkmcnt(0)
	v_pk_mul_f32 v[2:3], v[2:3], v[142:143]
	v_pk_mul_f32 v[0:1], v[0:1], v[140:141]
	v_pk_mul_f32 v[60:61], v[60:61], v[128:129]
	v_pk_mul_f32 v[56:57], v[56:57], v[132:133]
	v_pk_mul_f32 v[52:53], v[52:53], v[136:137]
	v_pk_mul_f32 v[62:63], v[62:63], v[130:131]
	v_pk_mul_f32 v[58:59], v[58:59], v[134:135]
	v_pk_mul_f32 v[54:55], v[54:55], v[138:139]
	v_pk_mul_f32 v[50:51], v[50:51], v[142:143]
	v_pk_mul_f32 v[48:49], v[48:49], v[140:141]
	v_pk_mul_f32 v[44:45], v[44:45], v[128:129]
	v_pk_mul_f32 v[40:41], v[40:41], v[132:133]
	v_pk_mul_f32 v[36:37], v[36:37], v[136:137]
	v_pk_mul_f32 v[46:47], v[46:47], v[130:131]
	v_pk_mul_f32 v[42:43], v[42:43], v[134:135]
	v_pk_mul_f32 v[38:39], v[38:39], v[138:139]
	v_pk_mul_f32 v[34:35], v[34:35], v[142:143]
	v_pk_mul_f32 v[32:33], v[32:33], v[140:141]
	v_pk_mul_f32 v[28:29], v[28:29], v[128:129]
	v_pk_mul_f32 v[24:25], v[24:25], v[132:133]
	v_pk_mul_f32 v[20:21], v[20:21], v[136:137]
	v_pk_mul_f32 v[30:31], v[30:31], v[130:131]
	v_pk_mul_f32 v[26:27], v[26:27], v[134:135]
	v_pk_mul_f32 v[22:23], v[22:23], v[138:139]
	v_pk_mul_f32 v[18:19], v[18:19], v[142:143]
	v_pk_mul_f32 v[16:17], v[16:17], v[140:141]
.LBB0_956:
	v_cndmask_b32_e64 v210, v149, v210, s[8:9]
	v_mul_f32_e32 v128, 0xbdd53b94, v210
	v_pk_fma_f32 v[80:81], v[80:81], s[78:79], v[128:129] op_sel_hi:[1,0,0]
	v_pk_fma_f32 v[82:83], v[82:83], s[78:79], v[128:129] op_sel_hi:[1,0,0]
	v_pk_fma_f32 v[84:85], v[84:85], s[78:79], v[128:129] op_sel_hi:[1,0,0]
	v_pk_fma_f32 v[86:87], v[86:87], s[78:79], v[128:129] op_sel_hi:[1,0,0]
	v_pk_fma_f32 v[88:89], v[88:89], s[78:79], v[128:129] op_sel_hi:[1,0,0]
	v_pk_fma_f32 v[90:91], v[90:91], s[78:79], v[128:129] op_sel_hi:[1,0,0]
	v_pk_fma_f32 v[92:93], v[92:93], s[78:79], v[128:129] op_sel_hi:[1,0,0]
	v_pk_fma_f32 v[94:95], v[94:95], s[78:79], v[128:129] op_sel_hi:[1,0,0]
	v_exp_f32_e32 v149, v80
	v_exp_f32_e32 v170, v81
	v_exp_f32_e32 v150, v82
	v_exp_f32_e32 v171, v83
	v_exp_f32_e32 v169, v84
	v_exp_f32_e32 v172, v85
	v_exp_f32_e32 v151, v86
	v_exp_f32_e32 v168, v87
	v_exp_f32_e32 v147, v88
	v_exp_f32_e32 v152, v89
	v_exp_f32_e32 v153, v90
	v_exp_f32_e32 v154, v91
	v_exp_f32_e32 v144, v92
	v_exp_f32_e32 v145, v93
	v_exp_f32_e32 v146, v94
	v_exp_f32_e32 v155, v95
	v_pk_fma_f32 v[142:143], v[64:65], s[78:79], v[128:129] op_sel_hi:[1,0,0]
	v_add_f32_e32 v64, v217, v218
	v_fmac_f32_e32 v64, v215, v180
	v_add_f32_e32 v180, v220, v221
	s_add_i32 s14, s14, 2
	v_pk_fma_f32 v[140:141], v[66:67], s[78:79], v[128:129] op_sel_hi:[1,0,0]
	v_pk_fma_f32 v[136:137], v[68:69], s[78:79], v[128:129] op_sel_hi:[1,0,0]
	v_pk_fma_f32 v[132:133], v[70:71], s[78:79], v[128:129] op_sel_hi:[1,0,0]
	v_pk_fma_f32 v[130:131], v[72:73], s[78:79], v[128:129] op_sel_hi:[1,0,0]
	v_pk_fma_f32 v[138:139], v[74:75], s[78:79], v[128:129] op_sel_hi:[1,0,0]
	v_pk_fma_f32 v[134:135], v[76:77], s[78:79], v[128:129] op_sel_hi:[1,0,0]
	v_pk_fma_f32 v[128:129], v[78:79], s[78:79], v[128:129] op_sel_hi:[1,0,0]
	v_fmac_f32_e32 v180, v64, v219
	s_add_u32 s56, s56, 0x30000
	s_addc_u32 s57, s57, 0
	s_add_u32 s32, s32, 0x20000
	s_addc_u32 s33, s33, 0
	s_cmp_ge_u32 s14, s23
	s_waitcnt lgkmcnt(0)
	s_barrier
	s_cbranch_scc1 .LBB0_958
	v_mov_b32_e32 v215, v148
	s_branch .LBB0_948
